# GEMM accumulator clearing with 64-bit moves (half the VALU slots per tile) on top of the barrier relocation + mixer wave priorities
# baseline (speedup 1.0000x reference)
; #define PG8_STAGE(bufoff, gbase, voff) do { _Pragma("unroll") for (int _i = 0; _i < 2; ++_i) \
;         __builtin_amdgcn_global_load_lds((const unsigned*)((const char*)(gbase) + (voff)[_i]), (LAS unsigned*)(lds + (bufoff) + ldsw + _i * 8192), 16, 0, 0); } while (0)
; #define PG8_LDA(dst, b, h) do { _Pragma("unroll") for (int m = 0; m < 4; ++m) _Pragma("unroll") for (int k = 0; k < 2; ++k) dst[m][k] = *(const LAS bf16x8*)(lds + PG8_SA(b, h) + aoff + m * 2048 + k * 1024); } while (0)
; #define PG8_LDB(dst, b, h) do { _Pragma("unroll") for (int n = 0; n < 2; ++n) _Pragma("unroll") for (int k = 0; k < 2; ++k) dst[n][k] = *(const LAS bf16x8*)(lds + PG8_SB(b, h) + boff + n * 2048 + k * 1024); } while (0)
; #define PG8_SCHED __builtin_amdgcn_sched_barrier(0)
; template <class Epi, bool ALIGN_EPI = PG8_ALIGN>
; __device__ __forceinline__ void gemm_phase(LAS unsigned char* lds, const Gemm g, const StaticOrder& S, const Epi& E) {
;     ...
;         const bool has_next = S.next(ui + 1, nxt);
;         const char* nA = has_next ? (const char*)g.A + (size_t)nxt.pm * tstepA : cA; const char* nB = has_next ? (const char*)g.Bt + (size_t)nxt.pn * tstepB : cB;
;         for (int t = 0; t < nt; t += 2) {
;             const bool last = (t == nt - 2);
;             const char* a1 = cA + (size_t)(t + 1) * kstep;
;             const char* a2 = last ? nA : cA + (size_t)(t + 2) * kstep; const char* b2 = last ? nB : cB + (size_t)(t + 2) * kstep;
;             const char* a3 = a2 + kstep; const char* b3 = b2 + kstep;
;             PG8_LDB(B0, 0, 0); PG8_LDB(B1, 0, 1); PG8_SCHED; PG8_LDA(At, 0, 0); PG8_STAGE(PG8_SA(1, 1), a1 + hstepA, voffA);
;     ...
; #pragma unroll
;         for (int a = 0; a < 2; ++a)
; #pragma unroll
;             for (int b = 0; b < 2; ++b)
; #pragma unroll
;                 for (int m = 0; m < 4; ++m)
; #pragma unroll
;                     for (int n = 0; n < 2; ++n) acc[a][b][m][n] = (f32x4){0.f, 0.f, 0.f, 0.f};
.LBB0_217:
	s_ashr_i32 s15, s14, 31
	s_lshl_b64 s[40:41], s[14:15], 20
	s_add_u32 s40, s58, s40
	v_mov_b32_e32 v127, 0
	s_addc_u32 s41, s59, s41
	s_andn2_b64 vcc, exec, s[10:11]
	v_mov_b32_e32 v126, v127
	v_mov_b32_e32 v125, v127
	v_mov_b32_e32 v124, v127
	v_mov_b32_e32 v119, v127
	v_mov_b32_e32 v118, v127
	v_mov_b32_e32 v117, v127
	v_mov_b32_e32 v116, v127
	v_mov_b32_e32 v111, v127
	v_mov_b32_e32 v110, v127
	v_mov_b32_e32 v109, v127
	v_mov_b32_e32 v108, v127
	v_mov_b32_e32 v103, v127
	v_mov_b32_e32 v102, v127
	v_mov_b32_e32 v101, v127
	v_mov_b32_e32 v100, v127
	v_mov_b32_e32 v95, v127
	v_mov_b32_e32 v94, v127
	v_mov_b32_e32 v93, v127
	v_mov_b32_e32 v92, v127
	v_mov_b32_e32 v87, v127
	v_mov_b32_e32 v86, v127
	v_mov_b32_e32 v85, v127
	v_mov_b32_e32 v84, v127
	v_mov_b32_e32 v79, v127
	v_mov_b32_e32 v78, v127
	v_mov_b32_e32 v77, v127
	v_mov_b32_e32 v76, v127
	v_mov_b32_e32 v71, v127
	v_mov_b32_e32 v70, v127
	v_mov_b32_e32 v69, v127
	v_mov_b32_e32 v68, v127
	v_mov_b32_e32 v123, v127
	v_mov_b32_e32 v122, v127
	v_mov_b32_e32 v121, v127
	v_mov_b32_e32 v120, v127
	v_mov_b32_e32 v115, v127
	v_mov_b32_e32 v114, v127
	v_mov_b32_e32 v113, v127
	v_mov_b32_e32 v112, v127
	v_mov_b32_e32 v107, v127
	v_mov_b32_e32 v106, v127
	v_mov_b32_e32 v105, v127
	v_mov_b32_e32 v104, v127
	v_mov_b32_e32 v99, v127
	v_mov_b32_e32 v98, v127
	v_mov_b32_e32 v97, v127
	v_mov_b32_e32 v96, v127
	v_mov_b32_e32 v91, v127
	v_mov_b32_e32 v90, v127
	v_mov_b32_e32 v89, v127
	v_mov_b32_e32 v88, v127
	v_mov_b32_e32 v83, v127
	v_mov_b32_e32 v82, v127
	v_mov_b32_e32 v81, v127
	v_mov_b32_e32 v80, v127
	v_mov_b32_e32 v75, v127
	v_mov_b32_e32 v74, v127
	v_mov_b32_e32 v73, v127
	v_mov_b32_e32 v72, v127
	v_mov_b32_e32 v67, v127
	v_mov_b32_e32 v66, v127
	v_mov_b32_e32 v65, v127
	v_mov_b32_e32 v64, v127
	v_mov_b32_e32 v63, v127
	v_mov_b32_e32 v62, v127
	v_mov_b32_e32 v61, v127
	v_mov_b32_e32 v60, v127
	v_mov_b32_e32 v55, v127
	v_mov_b32_e32 v54, v127
	v_mov_b32_e32 v53, v127
	v_mov_b32_e32 v52, v127
	v_mov_b32_e32 v47, v127
	v_mov_b32_e32 v46, v127
	v_mov_b32_e32 v45, v127
	v_mov_b32_e32 v44, v127
	v_mov_b32_e32 v39, v127
	v_mov_b32_e32 v38, v127
	v_mov_b32_e32 v37, v127
	v_mov_b32_e32 v36, v127
	v_mov_b32_e32 v31, v127
	v_mov_b32_e32 v30, v127
	v_mov_b32_e32 v29, v127
	v_mov_b32_e32 v28, v127
	v_mov_b32_e32 v23, v127
	v_mov_b32_e32 v22, v127
	v_mov_b32_e32 v21, v127
	v_mov_b32_e32 v20, v127
	v_mov_b32_e32 v15, v127
	v_mov_b32_e32 v14, v127
	v_mov_b32_e32 v13, v127
	v_mov_b32_e32 v12, v127
	v_mov_b32_e32 v7, v127
	v_mov_b32_e32 v6, v127
	v_mov_b32_e32 v5, v127
	v_mov_b32_e32 v4, v127
	v_mov_b32_e32 v59, v127
	v_mov_b32_e32 v58, v127
	v_mov_b32_e32 v57, v127
	v_mov_b32_e32 v56, v127
	v_mov_b32_e32 v51, v127
	v_mov_b32_e32 v50, v127
	v_mov_b32_e32 v49, v127
	v_mov_b32_e32 v48, v127
	v_mov_b32_e32 v43, v127
	v_mov_b32_e32 v42, v127
	v_mov_b32_e32 v41, v127
	v_mov_b32_e32 v40, v127
	v_mov_b32_e32 v35, v127
	v_mov_b32_e32 v34, v127
	v_mov_b32_e32 v33, v127
	v_mov_b32_e32 v32, v127
	v_mov_b32_e32 v27, v127
	v_mov_b32_e32 v26, v127
	v_mov_b32_e32 v25, v127
	v_mov_b32_e32 v24, v127
	v_mov_b32_e32 v19, v127
	v_mov_b32_e32 v18, v127
	v_mov_b32_e32 v17, v127
	v_mov_b32_e32 v16, v127
	v_mov_b32_e32 v11, v127
	v_mov_b32_e32 v10, v127
	v_mov_b32_e32 v9, v127
	v_mov_b32_e32 v8, v127
	v_mov_b32_e32 v3, v127
	v_mov_b32_e32 v2, v127
	v_mov_b32_e32 v1, v127
	v_mov_b32_e32 v0, v127
	s_cbranch_vccnz .LBB0_220
	s_and_b64 s[2:3], s[2:3], exec
	s_cselect_b32 s15, s41, s37
	s_cselect_b32 s34, s40, s36
	s_add_u32 s2, s36, 0x80080
	s_addc_u32 s3, s37, 0
	s_add_u32 s36, s24, 0x100
	v_mov_b32_e32 v0, 0
	s_addc_u32 s37, s25, 0
	s_mov_b32 s24, 0
	v_mov_b32_e32 v1, v0
	v_mov_b64_e32 v[2:3], 0
	v_mov_b64_e32 v[8:9], 0
	v_mov_b64_e32 v[10:11], 0
	v_mov_b64_e32 v[16:17], 0
	v_mov_b64_e32 v[18:19], 0
	v_mov_b64_e32 v[24:25], 0
	v_mov_b64_e32 v[26:27], 0
	v_mov_b64_e32 v[32:33], 0
	v_mov_b64_e32 v[34:35], 0
	v_mov_b64_e32 v[40:41], 0
	v_mov_b64_e32 v[42:43], 0
	v_mov_b64_e32 v[48:49], 0
	v_mov_b64_e32 v[50:51], 0
	v_mov_b64_e32 v[56:57], 0
	v_mov_b64_e32 v[58:59], 0
	v_mov_b64_e32 v[4:5], 0
	v_mov_b64_e32 v[6:7], 0
	v_mov_b64_e32 v[12:13], 0
	v_mov_b64_e32 v[14:15], 0
	v_mov_b64_e32 v[20:21], 0
	v_mov_b64_e32 v[22:23], 0
	v_mov_b64_e32 v[28:29], 0
	v_mov_b64_e32 v[30:31], 0
	v_mov_b64_e32 v[36:37], 0
	v_mov_b64_e32 v[38:39], 0
	v_mov_b64_e32 v[44:45], 0
	v_mov_b64_e32 v[46:47], 0
	v_mov_b64_e32 v[52:53], 0
	v_mov_b64_e32 v[54:55], 0
	v_mov_b64_e32 v[60:61], 0
	v_mov_b64_e32 v[62:63], 0
	v_mov_b64_e32 v[64:65], 0
	v_mov_b64_e32 v[66:67], 0
	v_mov_b64_e32 v[72:73], 0
	v_mov_b64_e32 v[74:75], 0
	v_mov_b64_e32 v[80:81], 0
	v_mov_b64_e32 v[82:83], 0
	v_mov_b64_e32 v[88:89], 0
	v_mov_b64_e32 v[90:91], 0
	v_mov_b64_e32 v[96:97], 0
	v_mov_b64_e32 v[98:99], 0
	v_mov_b64_e32 v[104:105], 0
	v_mov_b64_e32 v[106:107], 0
	v_mov_b64_e32 v[112:113], 0
	v_mov_b64_e32 v[114:115], 0
	v_mov_b64_e32 v[120:121], 0
	v_mov_b64_e32 v[122:123], 0
	v_mov_b64_e32 v[68:69], 0
	v_mov_b64_e32 v[70:71], 0
	v_mov_b64_e32 v[76:77], 0
	v_mov_b64_e32 v[78:79], 0
	v_mov_b64_e32 v[84:85], 0
	v_mov_b64_e32 v[86:87], 0
	v_mov_b64_e32 v[92:93], 0
	v_mov_b64_e32 v[94:95], 0
	v_mov_b64_e32 v[100:101], 0
	v_mov_b64_e32 v[102:103], 0
	v_mov_b64_e32 v[108:109], 0
	v_mov_b64_e32 v[110:111], 0
	v_mov_b64_e32 v[116:117], 0
	v_mov_b64_e32 v[118:119], 0
	v_mov_b64_e32 v[124:125], 0
	v_mov_b64_e32 v[126:127], 0

; template <class Epi, bool ALIGN_EPI = PG8_ALIGN>
; __device__ __forceinline__ void gemm_phase(LAS unsigned char* lds, const Gemm g, const StaticOrder& S, const Epi& E) {
;     ...
;         const bool has_next = S.next(ui + 1, nxt);
;         const char* nA = has_next ? (const char*)g.A + (size_t)nxt.pm * tstepA : cA; const char* nB = has_next ? (const char*)g.Bt + (size_t)nxt.pn * tstepB : cB;
;         for (int t = 0; t < nt; t += 2) {
;     ...
; #pragma unroll
;         for (int a = 0; a < 2; ++a)
; #pragma unroll
;             for (int b = 0; b < 2; ++b)
; #pragma unroll
;                 for (int m = 0; m < 4; ++m)
; #pragma unroll
;                     for (int n = 0; n < 2; ++n) acc[a][b][m][n] = (f32x4){0.f, 0.f, 0.f, 0.f};
.LBB0_293:
	v_mov_b32_e32 v127, 0
	s_andn2_b64 vcc, exec, s[12:13]
	v_mov_b32_e32 v126, 0
	v_mov_b32_e32 v125, 0
	v_mov_b32_e32 v124, 0
	v_mov_b32_e32 v123, 0
	v_mov_b32_e32 v122, 0
	v_mov_b32_e32 v121, 0
	v_mov_b32_e32 v120, 0
	v_mov_b32_e32 v101, 0
	v_mov_b32_e32 v100, 0
	v_mov_b32_e32 v103, 0
	v_mov_b32_e32 v102, 0
	v_mov_b32_e32 v109, 0
	v_mov_b32_e32 v108, 0
	v_mov_b32_e32 v111, 0
	v_mov_b32_e32 v110, 0
	v_mov_b32_e32 v85, 0
	v_mov_b32_e32 v84, 0
	v_mov_b32_e32 v87, 0
	v_mov_b32_e32 v86, 0
	v_mov_b32_e32 v93, 0
	v_mov_b32_e32 v92, 0
	v_mov_b32_e32 v95, 0
	v_mov_b32_e32 v94, 0
	v_mov_b32_e32 v73, 0
	v_mov_b32_e32 v72, 0
	v_mov_b32_e32 v75, 0
	v_mov_b32_e32 v74, 0
	v_mov_b32_e32 v77, 0
	v_mov_b32_e32 v76, 0
	v_mov_b32_e32 v79, 0
	v_mov_b32_e32 v78, 0
	v_mov_b32_e32 v139, 0
	v_mov_b32_e32 v138, 0
	v_mov_b32_e32 v141, 0
	v_mov_b32_e32 v140, 0
	v_mov_b32_e32 v143, 0
	v_mov_b32_e32 v142, 0
	v_mov_b32_e32 v145, 0
	v_mov_b32_e32 v144, 0
	v_mov_b32_e32 v113, 0
	v_mov_b32_e32 v112, 0
	v_mov_b32_e32 v115, 0
	v_mov_b32_e32 v114, 0
	v_mov_b32_e32 v117, 0
	v_mov_b32_e32 v116, 0
	v_mov_b32_e32 v119, 0
	v_mov_b32_e32 v118, 0
	v_mov_b32_e32 v97, 0
	v_mov_b32_e32 v96, 0
	v_mov_b32_e32 v99, 0
	v_mov_b32_e32 v98, 0
	v_mov_b32_e32 v105, 0
	v_mov_b32_e32 v104, 0
	v_mov_b32_e32 v107, 0
	v_mov_b32_e32 v106, 0
	v_mov_b32_e32 v71, 0
	v_mov_b32_e32 v70, 0
	v_mov_b32_e32 v69, 0
	v_mov_b32_e32 v68, 0
	v_mov_b32_e32 v67, 0
	v_mov_b32_e32 v66, 0
	v_mov_b32_e32 v65, 0
	v_mov_b32_e32 v64, 0
	v_mov_b32_e32 v63, 0
	v_mov_b32_e32 v62, 0
	v_mov_b32_e32 v61, 0
	v_mov_b32_e32 v60, 0
	v_mov_b32_e32 v59, 0
	v_mov_b32_e32 v58, 0
	v_mov_b32_e32 v57, 0
	v_mov_b32_e32 v56, 0
	v_mov_b32_e32 v37, 0
	v_mov_b32_e32 v36, 0
	v_mov_b32_e32 v39, 0
	v_mov_b32_e32 v38, 0
	v_mov_b32_e32 v45, 0
	v_mov_b32_e32 v44, 0
	v_mov_b32_e32 v47, 0
	v_mov_b32_e32 v46, 0
	v_mov_b32_e32 v21, 0
	v_mov_b32_e32 v20, 0
	v_mov_b32_e32 v23, 0
	v_mov_b32_e32 v22, 0
	v_mov_b32_e32 v29, 0
	v_mov_b32_e32 v28, 0
	v_mov_b32_e32 v31, 0
	v_mov_b32_e32 v30, 0
	v_mov_b32_e32 v9, 0
	v_mov_b32_e32 v8, 0
	v_mov_b32_e32 v11, 0
	v_mov_b32_e32 v10, 0
	v_mov_b32_e32 v13, 0
	v_mov_b32_e32 v12, 0
	v_mov_b32_e32 v15, 0
	v_mov_b32_e32 v14, 0
	v_mov_b32_e32 v81, 0
	v_mov_b32_e32 v80, 0
	v_mov_b32_e32 v83, 0
	v_mov_b32_e32 v82, 0
	v_mov_b32_e32 v89, 0
	v_mov_b32_e32 v88, 0
	v_mov_b32_e32 v91, 0
	v_mov_b32_e32 v90, 0
	v_mov_b32_e32 v49, 0
	v_mov_b32_e32 v48, 0
	v_mov_b32_e32 v51, 0
	v_mov_b32_e32 v50, 0
	v_mov_b32_e32 v53, 0
	v_mov_b32_e32 v52, 0
	v_mov_b32_e32 v55, 0
	v_mov_b32_e32 v54, 0
	v_mov_b32_e32 v33, 0
	v_mov_b32_e32 v32, 0
	v_mov_b32_e32 v35, 0
	v_mov_b32_e32 v34, 0
	v_mov_b32_e32 v41, 0
	v_mov_b32_e32 v40, 0
	v_mov_b32_e32 v43, 0
	v_mov_b32_e32 v42, 0
	v_mov_b32_e32 v7, 0
	v_mov_b32_e32 v6, 0
	v_mov_b32_e32 v5, 0
	v_mov_b32_e32 v4, 0
	v_mov_b32_e32 v3, 0
	v_mov_b32_e32 v2, 0
	v_mov_b32_e32 v1, 0
	v_mov_b32_e32 v0, 0
	s_cbranch_vccnz .LBB0_297
	s_add_u32 s51, s36, 0x100
	v_mov_b32_e32 v0, 0
	s_addc_u32 s52, s37, 0
	s_mov_b32 s38, 0
	v_mov_b32_e32 v1, v0
	v_mov_b64_e32 v[2:3], 0
	v_mov_b64_e32 v[4:5], 0
	v_mov_b64_e32 v[6:7], 0
	v_mov_b64_e32 v[8:9], 0
	v_mov_b64_e32 v[10:11], 0
	v_mov_b64_e32 v[12:13], 0
	v_mov_b64_e32 v[14:15], 0
	v_mov_b64_e32 v[20:21], 0
	v_mov_b64_e32 v[22:23], 0
	v_mov_b64_e32 v[28:29], 0
	v_mov_b64_e32 v[30:31], 0
	v_mov_b64_e32 v[36:37], 0
	v_mov_b64_e32 v[38:39], 0
	v_mov_b64_e32 v[44:45], 0
	v_mov_b64_e32 v[46:47], 0
	v_mov_b64_e32 v[16:17], 0
	v_mov_b64_e32 v[18:19], 0
	v_mov_b64_e32 v[24:25], 0
	v_mov_b64_e32 v[26:27], 0
	v_mov_b64_e32 v[32:33], 0
	v_mov_b64_e32 v[34:35], 0
	v_mov_b64_e32 v[40:41], 0
	v_mov_b64_e32 v[42:43], 0
	v_mov_b64_e32 v[48:49], 0
	v_mov_b64_e32 v[50:51], 0
	v_mov_b64_e32 v[52:53], 0
	v_mov_b64_e32 v[54:55], 0
	v_mov_b64_e32 v[56:57], 0
	v_mov_b64_e32 v[58:59], 0
	v_mov_b64_e32 v[60:61], 0
	v_mov_b64_e32 v[62:63], 0
	v_mov_b64_e32 v[64:65], 0
	v_mov_b64_e32 v[66:67], 0
	v_mov_b64_e32 v[68:69], 0
	v_mov_b64_e32 v[70:71], 0
	v_mov_b64_e32 v[72:73], 0
	v_mov_b64_e32 v[74:75], 0
	v_mov_b64_e32 v[76:77], 0
	v_mov_b64_e32 v[78:79], 0
	v_mov_b64_e32 v[84:85], 0
	v_mov_b64_e32 v[86:87], 0
	v_mov_b64_e32 v[92:93], 0
	v_mov_b64_e32 v[94:95], 0
	v_mov_b64_e32 v[100:101], 0
	v_mov_b64_e32 v[102:103], 0
	v_mov_b64_e32 v[108:109], 0
	v_mov_b64_e32 v[110:111], 0
	v_mov_b64_e32 v[80:81], 0
	v_mov_b64_e32 v[82:83], 0
	v_mov_b64_e32 v[88:89], 0
	v_mov_b64_e32 v[90:91], 0
	v_mov_b64_e32 v[96:97], 0
	v_mov_b64_e32 v[98:99], 0
	v_mov_b64_e32 v[104:105], 0
	v_mov_b64_e32 v[106:107], 0
	v_mov_b64_e32 v[112:113], 0
	v_mov_b64_e32 v[114:115], 0
	v_mov_b64_e32 v[116:117], 0
	v_mov_b64_e32 v[118:119], 0
	v_mov_b64_e32 v[120:121], 0
	v_mov_b64_e32 v[122:123], 0
	v_mov_b64_e32 v[124:125], 0
	v_mov_b64_e32 v[126:127], 0

; #define PG8_STAGE(bufoff, gbase, voff) do { _Pragma("unroll") for (int _i = 0; _i < 2; ++_i) \
;         __builtin_amdgcn_global_load_lds((const unsigned*)((const char*)(gbase) + (voff)[_i]), (LAS unsigned*)(lds + (bufoff) + ldsw + _i * 8192), 16, 0, 0); } while (0)
; #define PG8_LDA(dst, b, h) do { _Pragma("unroll") for (int m = 0; m < 4; ++m) _Pragma("unroll") for (int k = 0; k < 2; ++k) dst[m][k] = *(const LAS bf16x8*)(lds + PG8_SA(b, h) + aoff + m * 2048 + k * 1024); } while (0)
; #define PG8_LDB(dst, b, h) do { _Pragma("unroll") for (int n = 0; n < 2; ++n) _Pragma("unroll") for (int k = 0; k < 2; ++k) dst[n][k] = *(const LAS bf16x8*)(lds + PG8_SB(b, h) + boff + n * 2048 + k * 1024); } while (0)
; #define PG8_SCHED __builtin_amdgcn_sched_barrier(0)
; template <class Epi, bool ALIGN_EPI = PG8_ALIGN>
; __device__ __forceinline__ void gemm_phase(LAS unsigned char* lds, const Gemm g, const StaticOrder& S, const Epi& E) {
;     ...
;         const bool has_next = S.next(ui + 1, nxt);
;         const char* nA = has_next ? (const char*)g.A + (size_t)nxt.pm * tstepA : cA; const char* nB = has_next ? (const char*)g.Bt + (size_t)nxt.pn * tstepB : cB;
;         for (int t = 0; t < nt; t += 2) {
;             const bool last = (t == nt - 2);
;             const char* a1 = cA + (size_t)(t + 1) * kstep;
;             const char* a2 = last ? nA : cA + (size_t)(t + 2) * kstep; const char* b2 = last ? nB : cB + (size_t)(t + 2) * kstep;
;             const char* a3 = a2 + kstep; const char* b3 = b2 + kstep;
;             PG8_LDB(B0, 0, 0); PG8_LDB(B1, 0, 1); PG8_SCHED; PG8_LDA(At, 0, 0); PG8_STAGE(PG8_SA(1, 1), a1 + hstepA, voffA);
;     ...
; #pragma unroll
;         for (int a = 0; a < 2; ++a)
; #pragma unroll
;             for (int b = 0; b < 2; ++b)
; #pragma unroll
;                 for (int m = 0; m < 4; ++m)
; #pragma unroll
;                     for (int n = 0; n < 2; ++n) acc[a][b][m][n] = (f32x4){0.f, 0.f, 0.f, 0.f};
.LBB0_456:
	s_ashr_i32 s17, s16, 31
	s_lshl_b64 s[36:37], s[16:17], 20
	s_add_u32 s36, s58, s36
	v_mov_b32_e32 v123, 0
	s_addc_u32 s37, s59, s37
	s_andn2_b64 vcc, exec, s[12:13]
	v_mov_b32_e32 v122, v123
	v_mov_b32_e32 v121, v123
	v_mov_b32_e32 v120, v123
	v_mov_b32_e32 v127, v123
	v_mov_b32_e32 v126, v123
	v_mov_b32_e32 v125, v123
	v_mov_b32_e32 v124, v123
	v_mov_b32_e32 v111, v123
	v_mov_b32_e32 v110, v123
	v_mov_b32_e32 v109, v123
	v_mov_b32_e32 v108, v123
	v_mov_b32_e32 v107, v123
	v_mov_b32_e32 v106, v123
	v_mov_b32_e32 v105, v123
	v_mov_b32_e32 v104, v123
	v_mov_b32_e32 v95, v123
	v_mov_b32_e32 v94, v123
	v_mov_b32_e32 v93, v123
	v_mov_b32_e32 v92, v123
	v_mov_b32_e32 v91, v123
	v_mov_b32_e32 v90, v123
	v_mov_b32_e32 v89, v123
	v_mov_b32_e32 v88, v123
	v_mov_b32_e32 v79, v123
	v_mov_b32_e32 v78, v123
	v_mov_b32_e32 v77, v123
	v_mov_b32_e32 v76, v123
	v_mov_b32_e32 v75, v123
	v_mov_b32_e32 v74, v123
	v_mov_b32_e32 v73, v123
	v_mov_b32_e32 v72, v123
	v_mov_b32_e32 v119, v123
	v_mov_b32_e32 v118, v123
	v_mov_b32_e32 v117, v123
	v_mov_b32_e32 v116, v123
	v_mov_b32_e32 v115, v123
	v_mov_b32_e32 v114, v123
	v_mov_b32_e32 v113, v123
	v_mov_b32_e32 v112, v123
	v_mov_b32_e32 v103, v123
	v_mov_b32_e32 v102, v123
	v_mov_b32_e32 v101, v123
	v_mov_b32_e32 v100, v123
	v_mov_b32_e32 v99, v123
	v_mov_b32_e32 v98, v123
	v_mov_b32_e32 v97, v123
	v_mov_b32_e32 v96, v123
	v_mov_b32_e32 v87, v123
	v_mov_b32_e32 v86, v123
	v_mov_b32_e32 v85, v123
	v_mov_b32_e32 v84, v123
	v_mov_b32_e32 v83, v123
	v_mov_b32_e32 v82, v123
	v_mov_b32_e32 v81, v123
	v_mov_b32_e32 v80, v123
	v_mov_b32_e32 v71, v123
	v_mov_b32_e32 v70, v123
	v_mov_b32_e32 v69, v123
	v_mov_b32_e32 v68, v123
	v_mov_b32_e32 v67, v123
	v_mov_b32_e32 v66, v123
	v_mov_b32_e32 v65, v123
	v_mov_b32_e32 v64, v123
	v_mov_b32_e32 v63, v123
	v_mov_b32_e32 v62, v123
	v_mov_b32_e32 v61, v123
	v_mov_b32_e32 v60, v123
	v_mov_b32_e32 v59, v123
	v_mov_b32_e32 v58, v123
	v_mov_b32_e32 v57, v123
	v_mov_b32_e32 v56, v123
	v_mov_b32_e32 v47, v123
	v_mov_b32_e32 v46, v123
	v_mov_b32_e32 v45, v123
	v_mov_b32_e32 v44, v123
	v_mov_b32_e32 v43, v123
	v_mov_b32_e32 v42, v123
	v_mov_b32_e32 v41, v123
	v_mov_b32_e32 v40, v123
	v_mov_b32_e32 v31, v123
	v_mov_b32_e32 v30, v123
	v_mov_b32_e32 v29, v123
	v_mov_b32_e32 v28, v123
	v_mov_b32_e32 v27, v123
	v_mov_b32_e32 v26, v123
	v_mov_b32_e32 v25, v123
	v_mov_b32_e32 v24, v123
	v_mov_b32_e32 v15, v123
	v_mov_b32_e32 v14, v123
	v_mov_b32_e32 v13, v123
	v_mov_b32_e32 v12, v123
	v_mov_b32_e32 v11, v123
	v_mov_b32_e32 v10, v123
	v_mov_b32_e32 v9, v123
	v_mov_b32_e32 v8, v123
	v_mov_b32_e32 v55, v123
	v_mov_b32_e32 v54, v123
	v_mov_b32_e32 v53, v123
	v_mov_b32_e32 v52, v123
	v_mov_b32_e32 v51, v123
	v_mov_b32_e32 v50, v123
	v_mov_b32_e32 v49, v123
	v_mov_b32_e32 v48, v123
	v_mov_b32_e32 v39, v123
	v_mov_b32_e32 v38, v123
	v_mov_b32_e32 v37, v123
	v_mov_b32_e32 v36, v123
	v_mov_b32_e32 v35, v123
	v_mov_b32_e32 v34, v123
	v_mov_b32_e32 v33, v123
	v_mov_b32_e32 v32, v123
	v_mov_b32_e32 v23, v123
	v_mov_b32_e32 v22, v123
	v_mov_b32_e32 v21, v123
	v_mov_b32_e32 v20, v123
	v_mov_b32_e32 v19, v123
	v_mov_b32_e32 v18, v123
	v_mov_b32_e32 v17, v123
	v_mov_b32_e32 v16, v123
	v_mov_b32_e32 v7, v123
	v_mov_b32_e32 v6, v123
	v_mov_b32_e32 v5, v123
	v_mov_b32_e32 v4, v123
	v_mov_b32_e32 v3, v123
	v_mov_b32_e32 v2, v123
	v_mov_b32_e32 v1, v123
	v_mov_b32_e32 v0, v123
	s_cbranch_vccnz .LBB0_459
	s_and_b64 s[4:5], s[4:5], exec
	s_cselect_b32 s17, s37, s41
	s_cselect_b32 s50, s36, s40
	s_add_u32 s4, s40, 0x80080
	s_addc_u32 s5, s41, 0
	s_add_u32 s40, s38, 0x100
	v_mov_b32_e32 v0, 0
	s_addc_u32 s41, s39, 0
	s_mov_b32 s38, 0
	v_mov_b32_e32 v1, v0
	v_mov_b64_e32 v[2:3], 0
	v_mov_b64_e32 v[4:5], 0
	v_mov_b64_e32 v[6:7], 0
	v_mov_b64_e32 v[16:17], 0
	v_mov_b64_e32 v[18:19], 0
	v_mov_b64_e32 v[20:21], 0
	v_mov_b64_e32 v[22:23], 0
	v_mov_b64_e32 v[32:33], 0
	v_mov_b64_e32 v[34:35], 0
	v_mov_b64_e32 v[36:37], 0
	v_mov_b64_e32 v[38:39], 0
	v_mov_b64_e32 v[48:49], 0
	v_mov_b64_e32 v[50:51], 0
	v_mov_b64_e32 v[52:53], 0
	v_mov_b64_e32 v[54:55], 0
	v_mov_b64_e32 v[8:9], 0
	v_mov_b64_e32 v[10:11], 0
	v_mov_b64_e32 v[12:13], 0
	v_mov_b64_e32 v[14:15], 0
	v_mov_b64_e32 v[24:25], 0
	v_mov_b64_e32 v[26:27], 0
	v_mov_b64_e32 v[28:29], 0
	v_mov_b64_e32 v[30:31], 0
	v_mov_b64_e32 v[40:41], 0
	v_mov_b64_e32 v[42:43], 0
	v_mov_b64_e32 v[44:45], 0
	v_mov_b64_e32 v[46:47], 0
	v_mov_b64_e32 v[56:57], 0
	v_mov_b64_e32 v[58:59], 0
	v_mov_b64_e32 v[60:61], 0
	v_mov_b64_e32 v[62:63], 0
	v_mov_b64_e32 v[64:65], 0
	v_mov_b64_e32 v[66:67], 0
	v_mov_b64_e32 v[68:69], 0
	v_mov_b64_e32 v[70:71], 0
	v_mov_b64_e32 v[80:81], 0
	v_mov_b64_e32 v[82:83], 0
	v_mov_b64_e32 v[84:85], 0
	v_mov_b64_e32 v[86:87], 0
	v_mov_b64_e32 v[96:97], 0
	v_mov_b64_e32 v[98:99], 0
	v_mov_b64_e32 v[100:101], 0
	v_mov_b64_e32 v[102:103], 0
	v_mov_b64_e32 v[112:113], 0
	v_mov_b64_e32 v[114:115], 0
	v_mov_b64_e32 v[116:117], 0
	v_mov_b64_e32 v[118:119], 0
	v_mov_b64_e32 v[72:73], 0
	v_mov_b64_e32 v[74:75], 0
	v_mov_b64_e32 v[76:77], 0
	v_mov_b64_e32 v[78:79], 0
	v_mov_b64_e32 v[88:89], 0
	v_mov_b64_e32 v[90:91], 0
	v_mov_b64_e32 v[92:93], 0
	v_mov_b64_e32 v[94:95], 0
	v_mov_b64_e32 v[104:105], 0
	v_mov_b64_e32 v[106:107], 0
	v_mov_b64_e32 v[108:109], 0
	v_mov_b64_e32 v[110:111], 0
	v_mov_b64_e32 v[124:125], 0
	v_mov_b64_e32 v[126:127], 0
	v_mov_b64_e32 v[120:121], 0
	v_mov_b64_e32 v[122:123], 0

; #define PG8_STAGE(bufoff, gbase, voff) do { _Pragma("unroll") for (int _i = 0; _i < 2; ++_i) \
;         __builtin_amdgcn_global_load_lds((const unsigned*)((const char*)(gbase) + (voff)[_i]), (LAS unsigned*)(lds + (bufoff) + ldsw + _i * 8192), 16, 0, 0); } while (0)
; #define PG8_LDA(dst, b, h) do { _Pragma("unroll") for (int m = 0; m < 4; ++m) _Pragma("unroll") for (int k = 0; k < 2; ++k) dst[m][k] = *(const LAS bf16x8*)(lds + PG8_SA(b, h) + aoff + m * 2048 + k * 1024); } while (0)
; #define PG8_LDB(dst, b, h) do { _Pragma("unroll") for (int n = 0; n < 2; ++n) _Pragma("unroll") for (int k = 0; k < 2; ++k) dst[n][k] = *(const LAS bf16x8*)(lds + PG8_SB(b, h) + boff + n * 2048 + k * 1024); } while (0)
; #define PG8_SCHED __builtin_amdgcn_sched_barrier(0)
; template <class Epi, bool ALIGN_EPI = PG8_ALIGN>
; __device__ __forceinline__ void gemm_phase(LAS unsigned char* lds, const Gemm g, const StaticOrder& S, const Epi& E) {
;     ...
;         const bool has_next = S.next(ui + 1, nxt);
;         const char* nA = has_next ? (const char*)g.A + (size_t)nxt.pm * tstepA : cA; const char* nB = has_next ? (const char*)g.Bt + (size_t)nxt.pn * tstepB : cB;
;         for (int t = 0; t < nt; t += 2) {
;             const bool last = (t == nt - 2);
;             const char* a1 = cA + (size_t)(t + 1) * kstep;
;             const char* a2 = last ? nA : cA + (size_t)(t + 2) * kstep; const char* b2 = last ? nB : cB + (size_t)(t + 2) * kstep;
;             const char* a3 = a2 + kstep; const char* b3 = b2 + kstep;
;             PG8_LDB(B0, 0, 0); PG8_LDB(B1, 0, 1); PG8_SCHED; PG8_LDA(At, 0, 0); PG8_STAGE(PG8_SA(1, 1), a1 + hstepA, voffA);
;     ...
; #pragma unroll
;         for (int a = 0; a < 2; ++a)
; #pragma unroll
;             for (int b = 0; b < 2; ++b)
; #pragma unroll
;                 for (int m = 0; m < 4; ++m)
; #pragma unroll
;                     for (int n = 0; n < 2; ++n) acc[a][b][m][n] = (f32x4){0.f, 0.f, 0.f, 0.f};
.LBB0_479:
	s_ashr_i32 s17, s16, 31
	s_lshl_b64 s[36:37], s[16:17], 17
	s_add_u32 s36, s18, s36
	v_mov_b32_e32 v123, 0
	s_addc_u32 s37, s29, s37
	s_andn2_b64 vcc, exec, s[12:13]
	v_mov_b32_e32 v122, v123
	v_mov_b32_e32 v121, v123
	v_mov_b32_e32 v120, v123
	v_mov_b32_e32 v127, v123
	v_mov_b32_e32 v126, v123
	v_mov_b32_e32 v125, v123
	v_mov_b32_e32 v124, v123
	v_mov_b32_e32 v111, v123
	v_mov_b32_e32 v110, v123
	v_mov_b32_e32 v109, v123
	v_mov_b32_e32 v108, v123
	v_mov_b32_e32 v107, v123
	v_mov_b32_e32 v106, v123
	v_mov_b32_e32 v105, v123
	v_mov_b32_e32 v104, v123
	v_mov_b32_e32 v95, v123
	v_mov_b32_e32 v94, v123
	v_mov_b32_e32 v93, v123
	v_mov_b32_e32 v92, v123
	v_mov_b32_e32 v91, v123
	v_mov_b32_e32 v90, v123
	v_mov_b32_e32 v89, v123
	v_mov_b32_e32 v88, v123
	v_mov_b32_e32 v79, v123
	v_mov_b32_e32 v78, v123
	v_mov_b32_e32 v77, v123
	v_mov_b32_e32 v76, v123
	v_mov_b32_e32 v75, v123
	v_mov_b32_e32 v74, v123
	v_mov_b32_e32 v73, v123
	v_mov_b32_e32 v72, v123
	v_mov_b32_e32 v119, v123
	v_mov_b32_e32 v118, v123
	v_mov_b32_e32 v117, v123
	v_mov_b32_e32 v116, v123
	v_mov_b32_e32 v115, v123
	v_mov_b32_e32 v114, v123
	v_mov_b32_e32 v113, v123
	v_mov_b32_e32 v112, v123
	v_mov_b32_e32 v103, v123
	v_mov_b32_e32 v102, v123
	v_mov_b32_e32 v101, v123
	v_mov_b32_e32 v100, v123
	v_mov_b32_e32 v99, v123
	v_mov_b32_e32 v98, v123
	v_mov_b32_e32 v97, v123
	v_mov_b32_e32 v96, v123
	v_mov_b32_e32 v87, v123
	v_mov_b32_e32 v86, v123
	v_mov_b32_e32 v85, v123
	v_mov_b32_e32 v84, v123
	v_mov_b32_e32 v83, v123
	v_mov_b32_e32 v82, v123
	v_mov_b32_e32 v81, v123
	v_mov_b32_e32 v80, v123
	v_mov_b32_e32 v71, v123
	v_mov_b32_e32 v70, v123
	v_mov_b32_e32 v69, v123
	v_mov_b32_e32 v68, v123
	v_mov_b32_e32 v67, v123
	v_mov_b32_e32 v66, v123
	v_mov_b32_e32 v65, v123
	v_mov_b32_e32 v64, v123
	v_mov_b32_e32 v63, v123
	v_mov_b32_e32 v62, v123
	v_mov_b32_e32 v61, v123
	v_mov_b32_e32 v60, v123
	v_mov_b32_e32 v59, v123
	v_mov_b32_e32 v58, v123
	v_mov_b32_e32 v57, v123
	v_mov_b32_e32 v56, v123
	v_mov_b32_e32 v47, v123
	v_mov_b32_e32 v46, v123
	v_mov_b32_e32 v45, v123
	v_mov_b32_e32 v44, v123
	v_mov_b32_e32 v43, v123
	v_mov_b32_e32 v42, v123
	v_mov_b32_e32 v41, v123
	v_mov_b32_e32 v40, v123
	v_mov_b32_e32 v31, v123
	v_mov_b32_e32 v30, v123
	v_mov_b32_e32 v29, v123
	v_mov_b32_e32 v28, v123
	v_mov_b32_e32 v27, v123
	v_mov_b32_e32 v26, v123
	v_mov_b32_e32 v25, v123
	v_mov_b32_e32 v24, v123
	v_mov_b32_e32 v15, v123
	v_mov_b32_e32 v14, v123
	v_mov_b32_e32 v13, v123
	v_mov_b32_e32 v12, v123
	v_mov_b32_e32 v11, v123
	v_mov_b32_e32 v10, v123
	v_mov_b32_e32 v9, v123
	v_mov_b32_e32 v8, v123
	v_mov_b32_e32 v55, v123
	v_mov_b32_e32 v54, v123
	v_mov_b32_e32 v53, v123
	v_mov_b32_e32 v52, v123
	v_mov_b32_e32 v51, v123
	v_mov_b32_e32 v50, v123
	v_mov_b32_e32 v49, v123
	v_mov_b32_e32 v48, v123
	v_mov_b32_e32 v39, v123
	v_mov_b32_e32 v38, v123
	v_mov_b32_e32 v37, v123
	v_mov_b32_e32 v36, v123
	v_mov_b32_e32 v35, v123
	v_mov_b32_e32 v34, v123
	v_mov_b32_e32 v33, v123
	v_mov_b32_e32 v32, v123
	v_mov_b32_e32 v23, v123
	v_mov_b32_e32 v22, v123
	v_mov_b32_e32 v21, v123
	v_mov_b32_e32 v20, v123
	v_mov_b32_e32 v19, v123
	v_mov_b32_e32 v18, v123
	v_mov_b32_e32 v17, v123
	v_mov_b32_e32 v16, v123
	v_mov_b32_e32 v7, v123
	v_mov_b32_e32 v6, v123
	v_mov_b32_e32 v5, v123
	v_mov_b32_e32 v4, v123
	v_mov_b32_e32 v3, v123
	v_mov_b32_e32 v2, v123
	v_mov_b32_e32 v1, v123
	v_mov_b32_e32 v0, v123
	s_cbranch_vccnz .LBB0_482
	s_and_b64 s[4:5], s[4:5], exec
	s_cselect_b32 s17, s37, s41
	s_cselect_b32 s52, s36, s40
	s_add_u32 s4, s40, 0x10080
	s_addc_u32 s5, s41, 0
	s_add_u32 s40, s38, 0x100
	v_mov_b32_e32 v0, 0
	s_addc_u32 s41, s39, 0
	s_mov_b32 s38, 0
	v_mov_b32_e32 v1, v0
	v_mov_b64_e32 v[2:3], 0
	v_mov_b64_e32 v[4:5], 0
	v_mov_b64_e32 v[6:7], 0
	v_mov_b64_e32 v[16:17], 0
	v_mov_b64_e32 v[18:19], 0
	v_mov_b64_e32 v[20:21], 0
	v_mov_b64_e32 v[22:23], 0
	v_mov_b64_e32 v[32:33], 0
	v_mov_b64_e32 v[34:35], 0
	v_mov_b64_e32 v[36:37], 0
	v_mov_b64_e32 v[38:39], 0
	v_mov_b64_e32 v[48:49], 0
	v_mov_b64_e32 v[50:51], 0
	v_mov_b64_e32 v[52:53], 0
	v_mov_b64_e32 v[54:55], 0
	v_mov_b64_e32 v[8:9], 0
	v_mov_b64_e32 v[10:11], 0
	v_mov_b64_e32 v[12:13], 0
	v_mov_b64_e32 v[14:15], 0
	v_mov_b64_e32 v[24:25], 0
	v_mov_b64_e32 v[26:27], 0
	v_mov_b64_e32 v[28:29], 0
	v_mov_b64_e32 v[30:31], 0
	v_mov_b64_e32 v[40:41], 0
	v_mov_b64_e32 v[42:43], 0
	v_mov_b64_e32 v[44:45], 0
	v_mov_b64_e32 v[46:47], 0
	v_mov_b64_e32 v[56:57], 0
	v_mov_b64_e32 v[58:59], 0
	v_mov_b64_e32 v[60:61], 0
	v_mov_b64_e32 v[62:63], 0
	v_mov_b64_e32 v[64:65], 0
	v_mov_b64_e32 v[66:67], 0
	v_mov_b64_e32 v[68:69], 0
	v_mov_b64_e32 v[70:71], 0
	v_mov_b64_e32 v[80:81], 0
	v_mov_b64_e32 v[82:83], 0
	v_mov_b64_e32 v[84:85], 0
	v_mov_b64_e32 v[86:87], 0
	v_mov_b64_e32 v[96:97], 0
	v_mov_b64_e32 v[98:99], 0
	v_mov_b64_e32 v[100:101], 0
	v_mov_b64_e32 v[102:103], 0
	v_mov_b64_e32 v[112:113], 0
	v_mov_b64_e32 v[114:115], 0
	v_mov_b64_e32 v[116:117], 0
	v_mov_b64_e32 v[118:119], 0
	v_mov_b64_e32 v[72:73], 0
	v_mov_b64_e32 v[74:75], 0
	v_mov_b64_e32 v[76:77], 0
	v_mov_b64_e32 v[78:79], 0
	v_mov_b64_e32 v[88:89], 0
	v_mov_b64_e32 v[90:91], 0
	v_mov_b64_e32 v[92:93], 0
	v_mov_b64_e32 v[94:95], 0
	v_mov_b64_e32 v[104:105], 0
	v_mov_b64_e32 v[106:107], 0
	v_mov_b64_e32 v[108:109], 0
	v_mov_b64_e32 v[110:111], 0
	v_mov_b64_e32 v[124:125], 0
	v_mov_b64_e32 v[126:127], 0
	v_mov_b64_e32 v[120:121], 0
	v_mov_b64_e32 v[122:123], 0

; template <class Epi, bool ALIGN_EPI = PG8_ALIGN>
; __device__ __forceinline__ void gemm_phase(LAS unsigned char* lds, const Gemm g, const StaticOrder& S, const Epi& E) {
;     ...
;         const bool has_next = S.next(ui + 1, nxt);
;         const char* nA = has_next ? (const char*)g.A + (size_t)nxt.pm * tstepA : cA; const char* nB = has_next ? (const char*)g.Bt + (size_t)nxt.pn * tstepB : cB;
;         for (int t = 0; t < nt; t += 2) {
;     ...
; #pragma unroll
;         for (int a = 0; a < 2; ++a)
; #pragma unroll
;             for (int b = 0; b < 2; ++b)
; #pragma unroll
;                 for (int m = 0; m < 4; ++m)
; #pragma unroll
;                     for (int n = 0; n < 2; ++n) acc[a][b][m][n] = (f32x4){0.f, 0.f, 0.f, 0.f};
.LBB0_640:
	v_mov_b32_e32 v123, 0
	s_andn2_b64 vcc, exec, s[12:13]
	v_mov_b32_e32 v122, v123
	v_mov_b32_e32 v121, v123
	v_mov_b32_e32 v120, v123
	v_mov_b32_e32 v127, v123
	v_mov_b32_e32 v126, v123
	v_mov_b32_e32 v125, v123
	v_mov_b32_e32 v124, v123
	v_mov_b32_e32 v111, v123
	v_mov_b32_e32 v110, v123
	v_mov_b32_e32 v109, v123
	v_mov_b32_e32 v108, v123
	v_mov_b32_e32 v107, v123
	v_mov_b32_e32 v106, v123
	v_mov_b32_e32 v105, v123
	v_mov_b32_e32 v104, v123
	v_mov_b32_e32 v95, v123
	v_mov_b32_e32 v94, v123
	v_mov_b32_e32 v93, v123
	v_mov_b32_e32 v92, v123
	v_mov_b32_e32 v91, v123
	v_mov_b32_e32 v90, v123
	v_mov_b32_e32 v89, v123
	v_mov_b32_e32 v88, v123
	v_mov_b32_e32 v79, v123
	v_mov_b32_e32 v78, v123
	v_mov_b32_e32 v77, v123
	v_mov_b32_e32 v76, v123
	v_mov_b32_e32 v75, v123
	v_mov_b32_e32 v74, v123
	v_mov_b32_e32 v73, v123
	v_mov_b32_e32 v72, v123
	v_mov_b32_e32 v119, v123
	v_mov_b32_e32 v118, v123
	v_mov_b32_e32 v117, v123
	v_mov_b32_e32 v116, v123
	v_mov_b32_e32 v115, v123
	v_mov_b32_e32 v114, v123
	v_mov_b32_e32 v113, v123
	v_mov_b32_e32 v112, v123
	v_mov_b32_e32 v103, v123
	v_mov_b32_e32 v102, v123
	v_mov_b32_e32 v101, v123
	v_mov_b32_e32 v100, v123
	v_mov_b32_e32 v99, v123
	v_mov_b32_e32 v98, v123
	v_mov_b32_e32 v97, v123
	v_mov_b32_e32 v96, v123
	v_mov_b32_e32 v87, v123
	v_mov_b32_e32 v86, v123
	v_mov_b32_e32 v85, v123
	v_mov_b32_e32 v84, v123
	v_mov_b32_e32 v83, v123
	v_mov_b32_e32 v82, v123
	v_mov_b32_e32 v81, v123
	v_mov_b32_e32 v80, v123
	v_mov_b32_e32 v71, v123
	v_mov_b32_e32 v70, v123
	v_mov_b32_e32 v69, v123
	v_mov_b32_e32 v68, v123
	v_mov_b32_e32 v67, v123
	v_mov_b32_e32 v66, v123
	v_mov_b32_e32 v65, v123
	v_mov_b32_e32 v64, v123
	v_mov_b32_e32 v63, v123
	v_mov_b32_e32 v62, v123
	v_mov_b32_e32 v61, v123
	v_mov_b32_e32 v60, v123
	v_mov_b32_e32 v59, v123
	v_mov_b32_e32 v58, v123
	v_mov_b32_e32 v57, v123
	v_mov_b32_e32 v56, v123
	v_mov_b32_e32 v47, v123
	v_mov_b32_e32 v46, v123
	v_mov_b32_e32 v45, v123
	v_mov_b32_e32 v44, v123
	v_mov_b32_e32 v43, v123
	v_mov_b32_e32 v42, v123
	v_mov_b32_e32 v41, v123
	v_mov_b32_e32 v40, v123
	v_mov_b32_e32 v31, v123
	v_mov_b32_e32 v30, v123
	v_mov_b32_e32 v29, v123
	v_mov_b32_e32 v28, v123
	v_mov_b32_e32 v27, v123
	v_mov_b32_e32 v26, v123
	v_mov_b32_e32 v25, v123
	v_mov_b32_e32 v24, v123
	v_mov_b32_e32 v15, v123
	v_mov_b32_e32 v14, v123
	v_mov_b32_e32 v13, v123
	v_mov_b32_e32 v12, v123
	v_mov_b32_e32 v11, v123
	v_mov_b32_e32 v10, v123
	v_mov_b32_e32 v9, v123
	v_mov_b32_e32 v8, v123
	v_mov_b32_e32 v55, v123
	v_mov_b32_e32 v54, v123
	v_mov_b32_e32 v53, v123
	v_mov_b32_e32 v52, v123
	v_mov_b32_e32 v51, v123
	v_mov_b32_e32 v50, v123
	v_mov_b32_e32 v49, v123
	v_mov_b32_e32 v48, v123
	v_mov_b32_e32 v39, v123
	v_mov_b32_e32 v38, v123
	v_mov_b32_e32 v37, v123
	v_mov_b32_e32 v36, v123
	v_mov_b32_e32 v35, v123
	v_mov_b32_e32 v34, v123
	v_mov_b32_e32 v33, v123
	v_mov_b32_e32 v32, v123
	v_mov_b32_e32 v23, v123
	v_mov_b32_e32 v22, v123
	v_mov_b32_e32 v21, v123
	v_mov_b32_e32 v20, v123
	v_mov_b32_e32 v19, v123
	v_mov_b32_e32 v18, v123
	v_mov_b32_e32 v17, v123
	v_mov_b32_e32 v16, v123
	v_mov_b32_e32 v7, v123
	v_mov_b32_e32 v6, v123
	v_mov_b32_e32 v5, v123
	v_mov_b32_e32 v4, v123
	v_mov_b32_e32 v3, v123
	v_mov_b32_e32 v2, v123
	v_mov_b32_e32 v1, v123
	v_mov_b32_e32 v0, v123
	s_cbranch_vccnz .LBB0_643
	s_add_u32 s51, s36, 0x100
	v_mov_b32_e32 v0, 0
	s_addc_u32 s52, s37, 0
	s_mov_b32 s38, 0
	v_mov_b32_e32 v1, v0
	v_mov_b64_e32 v[2:3], 0
	v_mov_b64_e32 v[4:5], 0
	v_mov_b64_e32 v[6:7], 0
	v_mov_b64_e32 v[16:17], 0
	v_mov_b64_e32 v[18:19], 0
	v_mov_b64_e32 v[20:21], 0
	v_mov_b64_e32 v[22:23], 0
	v_mov_b64_e32 v[32:33], 0
	v_mov_b64_e32 v[34:35], 0
	v_mov_b64_e32 v[36:37], 0
	v_mov_b64_e32 v[38:39], 0
	v_mov_b64_e32 v[48:49], 0
	v_mov_b64_e32 v[50:51], 0
	v_mov_b64_e32 v[52:53], 0
	v_mov_b64_e32 v[54:55], 0
	v_mov_b64_e32 v[8:9], 0
	v_mov_b64_e32 v[10:11], 0
	v_mov_b64_e32 v[12:13], 0
	v_mov_b64_e32 v[14:15], 0
	v_mov_b64_e32 v[24:25], 0
	v_mov_b64_e32 v[26:27], 0
	v_mov_b64_e32 v[28:29], 0
	v_mov_b64_e32 v[30:31], 0
	v_mov_b64_e32 v[40:41], 0
	v_mov_b64_e32 v[42:43], 0
	v_mov_b64_e32 v[44:45], 0
	v_mov_b64_e32 v[46:47], 0
	v_mov_b64_e32 v[56:57], 0
	v_mov_b64_e32 v[58:59], 0
	v_mov_b64_e32 v[60:61], 0
	v_mov_b64_e32 v[62:63], 0
	v_mov_b64_e32 v[64:65], 0
	v_mov_b64_e32 v[66:67], 0
	v_mov_b64_e32 v[68:69], 0
	v_mov_b64_e32 v[70:71], 0
	v_mov_b64_e32 v[80:81], 0
	v_mov_b64_e32 v[82:83], 0
	v_mov_b64_e32 v[84:85], 0
	v_mov_b64_e32 v[86:87], 0
	v_mov_b64_e32 v[96:97], 0
	v_mov_b64_e32 v[98:99], 0
	v_mov_b64_e32 v[100:101], 0
	v_mov_b64_e32 v[102:103], 0
	v_mov_b64_e32 v[112:113], 0
	v_mov_b64_e32 v[114:115], 0
	v_mov_b64_e32 v[116:117], 0
	v_mov_b64_e32 v[118:119], 0
	v_mov_b64_e32 v[72:73], 0
	v_mov_b64_e32 v[74:75], 0
	v_mov_b64_e32 v[76:77], 0
	v_mov_b64_e32 v[78:79], 0
	v_mov_b64_e32 v[88:89], 0
	v_mov_b64_e32 v[90:91], 0
	v_mov_b64_e32 v[92:93], 0
	v_mov_b64_e32 v[94:95], 0
	v_mov_b64_e32 v[104:105], 0
	v_mov_b64_e32 v[106:107], 0
	v_mov_b64_e32 v[108:109], 0
	v_mov_b64_e32 v[110:111], 0
	v_mov_b64_e32 v[124:125], 0
	v_mov_b64_e32 v[126:127], 0
	v_mov_b64_e32 v[120:121], 0
	v_mov_b64_e32 v[122:123], 0

; #define PG8_STAGE(bufoff, gbase, voff) do { _Pragma("unroll") for (int _i = 0; _i < 2; ++_i) \
;         __builtin_amdgcn_global_load_lds((const unsigned*)((const char*)(gbase) + (voff)[_i]), (LAS unsigned*)(lds + (bufoff) + ldsw + _i * 8192), 16, 0, 0); } while (0)
; #define PG8_WAIT_V(n) asm volatile("s_waitcnt vmcnt(" #n ")" ::: "memory")
; #define PG8_BAR __builtin_amdgcn_s_barrier()
; template <class Epi, bool ALIGN_EPI = PG8_ALIGN>
; __device__ __forceinline__ void gemm_phase(LAS unsigned char* lds, const Gemm g, const StaticOrder& S, const Epi& E) {
;     ...
;     f32x4 acc[2][2][4][2];
; #pragma unroll
;     for (int a = 0; a < 2; ++a)
; #pragma unroll
;         for (int b = 0; b < 2; ++b)
; #pragma unroll
;             for (int m = 0; m < 4; ++m)
; #pragma unroll
;                 for (int n = 0; n < 2; ++n) acc[a][b][m][n] = (f32x4){0.f, 0.f, 0.f, 0.f};
;     bf16x8 At[4][2], B0[2][2], B1[2][2];
;     const char* cA = (const char*)g.A + (size_t)cur.pm * tstepA; const char* cB = (const char*)g.Bt + (size_t)cur.pn * tstepB;
;     PG8_STAGE(PG8_SB(0, 0), cB, voffB); PG8_STAGE(PG8_SB(0, 1), cB + hstepB, voffB); PG8_STAGE(PG8_SA(0, 0), cA, voffA); PG8_STAGE(PG8_SA(0, 1), cA + hstepA, voffA);
;     if (wr == 1) PG8_BAR;
;     PG8_WAIT_V(2); PG8_BAR;
;     PG8_STAGE(PG8_SB(1, 0), cB + kstep, voffB); PG8_STAGE(PG8_SA(1, 0), cA + kstep, voffA); PG8_STAGE(PG8_SB(1, 1), cB + hstepB + kstep, voffB);
;     PG8_WAIT_V(6); PG8_BAR;
;     for (;;) {
;         const bool has_next = S.next(ui + 1, nxt);
;         const char* nA = has_next ? (const char*)g.A + (size_t)nxt.pm * tstepA : cA; const char* nB = has_next ? (const char*)g.Bt + (size_t)nxt.pn * tstepB : cB;
;     ...
; #pragma unroll
;         for (int a = 0; a < 2; ++a)
; #pragma unroll
;             for (int b = 0; b < 2; ++b)
; #pragma unroll
;                 for (int m = 0; m < 4; ++m)
; #pragma unroll
;                     for (int n = 0; n < 2; ++n) acc[a][b][m][n] = (f32x4){0.f, 0.f, 0.f, 0.f};
;         cur = nxt; cA = nA; cB = nB; ++ui;
.LBB0_661:
	v_mov_b32_e32 v123, 0
	s_andn2_b64 vcc, exec, s[12:13]
	v_mov_b32_e32 v122, v123
	v_mov_b32_e32 v121, v123
	v_mov_b32_e32 v120, v123
	v_mov_b32_e32 v127, v123
	v_mov_b32_e32 v126, v123
	v_mov_b32_e32 v125, v123
	v_mov_b32_e32 v124, v123
	v_mov_b32_e32 v111, v123
	v_mov_b32_e32 v110, v123
	v_mov_b32_e32 v109, v123
	v_mov_b32_e32 v108, v123
	v_mov_b32_e32 v107, v123
	v_mov_b32_e32 v106, v123
	v_mov_b32_e32 v105, v123
	v_mov_b32_e32 v104, v123
	v_mov_b32_e32 v95, v123
	v_mov_b32_e32 v94, v123
	v_mov_b32_e32 v93, v123
	v_mov_b32_e32 v92, v123
	v_mov_b32_e32 v91, v123
	v_mov_b32_e32 v90, v123
	v_mov_b32_e32 v89, v123
	v_mov_b32_e32 v88, v123
	v_mov_b32_e32 v79, v123
	v_mov_b32_e32 v78, v123
	v_mov_b32_e32 v77, v123
	v_mov_b32_e32 v76, v123
	v_mov_b32_e32 v75, v123
	v_mov_b32_e32 v74, v123
	v_mov_b32_e32 v73, v123
	v_mov_b32_e32 v72, v123
	v_mov_b32_e32 v119, v123
	v_mov_b32_e32 v118, v123
	v_mov_b32_e32 v117, v123
	v_mov_b32_e32 v116, v123
	v_mov_b32_e32 v115, v123
	v_mov_b32_e32 v114, v123
	v_mov_b32_e32 v113, v123
	v_mov_b32_e32 v112, v123
	v_mov_b32_e32 v103, v123
	v_mov_b32_e32 v102, v123
	v_mov_b32_e32 v101, v123
	v_mov_b32_e32 v100, v123
	v_mov_b32_e32 v99, v123
	v_mov_b32_e32 v98, v123
	v_mov_b32_e32 v97, v123
	v_mov_b32_e32 v96, v123
	v_mov_b32_e32 v87, v123
	v_mov_b32_e32 v86, v123
	v_mov_b32_e32 v85, v123
	v_mov_b32_e32 v84, v123
	v_mov_b32_e32 v83, v123
	v_mov_b32_e32 v82, v123
	v_mov_b32_e32 v81, v123
	v_mov_b32_e32 v80, v123
	v_mov_b32_e32 v71, v123
	v_mov_b32_e32 v70, v123
	v_mov_b32_e32 v69, v123
	v_mov_b32_e32 v68, v123
	v_mov_b32_e32 v67, v123
	v_mov_b32_e32 v66, v123
	v_mov_b32_e32 v65, v123
	v_mov_b32_e32 v64, v123
	v_mov_b32_e32 v63, v123
	v_mov_b32_e32 v62, v123
	v_mov_b32_e32 v61, v123
	v_mov_b32_e32 v60, v123
	v_mov_b32_e32 v59, v123
	v_mov_b32_e32 v58, v123
	v_mov_b32_e32 v57, v123
	v_mov_b32_e32 v56, v123
	v_mov_b32_e32 v47, v123
	v_mov_b32_e32 v46, v123
	v_mov_b32_e32 v45, v123
	v_mov_b32_e32 v44, v123
	v_mov_b32_e32 v43, v123
	v_mov_b32_e32 v42, v123
	v_mov_b32_e32 v41, v123
	v_mov_b32_e32 v40, v123
	v_mov_b32_e32 v31, v123
	v_mov_b32_e32 v30, v123
	v_mov_b32_e32 v29, v123
	v_mov_b32_e32 v28, v123
	v_mov_b32_e32 v27, v123
	v_mov_b32_e32 v26, v123
	v_mov_b32_e32 v25, v123
	v_mov_b32_e32 v24, v123
	v_mov_b32_e32 v15, v123
	v_mov_b32_e32 v14, v123
	v_mov_b32_e32 v13, v123
	v_mov_b32_e32 v12, v123
	v_mov_b32_e32 v11, v123
	v_mov_b32_e32 v10, v123
	v_mov_b32_e32 v9, v123
	v_mov_b32_e32 v8, v123
	v_mov_b32_e32 v55, v123
	v_mov_b32_e32 v54, v123
	v_mov_b32_e32 v53, v123
	v_mov_b32_e32 v52, v123
	v_mov_b32_e32 v51, v123
	v_mov_b32_e32 v50, v123
	v_mov_b32_e32 v49, v123
	v_mov_b32_e32 v48, v123
	v_mov_b32_e32 v39, v123
	v_mov_b32_e32 v38, v123
	v_mov_b32_e32 v37, v123
	v_mov_b32_e32 v36, v123
	v_mov_b32_e32 v35, v123
	v_mov_b32_e32 v34, v123
	v_mov_b32_e32 v33, v123
	v_mov_b32_e32 v32, v123
	v_mov_b32_e32 v23, v123
	v_mov_b32_e32 v22, v123
	v_mov_b32_e32 v21, v123
	v_mov_b32_e32 v20, v123
	v_mov_b32_e32 v19, v123
	v_mov_b32_e32 v18, v123
	v_mov_b32_e32 v17, v123
	v_mov_b32_e32 v16, v123
	v_mov_b32_e32 v7, v123
	v_mov_b32_e32 v6, v123
	v_mov_b32_e32 v5, v123
	v_mov_b32_e32 v4, v123
	v_mov_b32_e32 v3, v123
	v_mov_b32_e32 v2, v123
	v_mov_b32_e32 v1, v123
	v_mov_b32_e32 v0, v123
	s_cbranch_vccnz .LBB0_664
	s_add_u32 s34, s36, 0x100
	v_mov_b32_e32 v0, 0
	s_addc_u32 s52, s37, 0
	s_mov_b32 s38, 0
	v_mov_b32_e32 v1, v0
	v_mov_b64_e32 v[2:3], 0
	v_mov_b64_e32 v[4:5], 0
	v_mov_b64_e32 v[6:7], 0
	v_mov_b64_e32 v[16:17], 0
	v_mov_b64_e32 v[18:19], 0
	v_mov_b64_e32 v[20:21], 0
	v_mov_b64_e32 v[22:23], 0
	v_mov_b64_e32 v[32:33], 0
	v_mov_b64_e32 v[34:35], 0
	v_mov_b64_e32 v[36:37], 0
	v_mov_b64_e32 v[38:39], 0
	v_mov_b64_e32 v[48:49], 0
	v_mov_b64_e32 v[50:51], 0
	v_mov_b64_e32 v[52:53], 0
	v_mov_b64_e32 v[54:55], 0
	v_mov_b64_e32 v[8:9], 0
	v_mov_b64_e32 v[10:11], 0
	v_mov_b64_e32 v[12:13], 0
	v_mov_b64_e32 v[14:15], 0
	v_mov_b64_e32 v[24:25], 0
	v_mov_b64_e32 v[26:27], 0
	v_mov_b64_e32 v[28:29], 0
	v_mov_b64_e32 v[30:31], 0
	v_mov_b64_e32 v[40:41], 0
	v_mov_b64_e32 v[42:43], 0
	v_mov_b64_e32 v[44:45], 0
	v_mov_b64_e32 v[46:47], 0
	v_mov_b64_e32 v[56:57], 0
	v_mov_b64_e32 v[58:59], 0
	v_mov_b64_e32 v[60:61], 0
	v_mov_b64_e32 v[62:63], 0
	v_mov_b64_e32 v[64:65], 0
	v_mov_b64_e32 v[66:67], 0
	v_mov_b64_e32 v[68:69], 0
	v_mov_b64_e32 v[70:71], 0
	v_mov_b64_e32 v[80:81], 0
	v_mov_b64_e32 v[82:83], 0
	v_mov_b64_e32 v[84:85], 0
	v_mov_b64_e32 v[86:87], 0
	v_mov_b64_e32 v[96:97], 0
	v_mov_b64_e32 v[98:99], 0
	v_mov_b64_e32 v[100:101], 0
	v_mov_b64_e32 v[102:103], 0
	v_mov_b64_e32 v[112:113], 0
	v_mov_b64_e32 v[114:115], 0
	v_mov_b64_e32 v[116:117], 0
	v_mov_b64_e32 v[118:119], 0
	v_mov_b64_e32 v[72:73], 0
	v_mov_b64_e32 v[74:75], 0
	v_mov_b64_e32 v[76:77], 0
	v_mov_b64_e32 v[78:79], 0
	v_mov_b64_e32 v[88:89], 0
	v_mov_b64_e32 v[90:91], 0
	v_mov_b64_e32 v[92:93], 0
	v_mov_b64_e32 v[94:95], 0
	v_mov_b64_e32 v[104:105], 0
	v_mov_b64_e32 v[106:107], 0
	v_mov_b64_e32 v[108:109], 0
	v_mov_b64_e32 v[110:111], 0
	v_mov_b64_e32 v[124:125], 0
	v_mov_b64_e32 v[126:127], 0
	v_mov_b64_e32 v[120:121], 0
	v_mov_b64_e32 v[122:123], 0

; #define PG8_STAGE(bufoff, gbase, voff) do { _Pragma("unroll") for (int _i = 0; _i < 2; ++_i) \
;         __builtin_amdgcn_global_load_lds((const unsigned*)((const char*)(gbase) + (voff)[_i]), (LAS unsigned*)(lds + (bufoff) + ldsw + _i * 8192), 16, 0, 0); } while (0)
; #define PG8_WAIT_V(n) asm volatile("s_waitcnt vmcnt(" #n ")" ::: "memory")
; #define PG8_BAR __builtin_amdgcn_s_barrier()
; template <class Epi, bool ALIGN_EPI = PG8_ALIGN>
; __device__ __forceinline__ void gemm_phase(LAS unsigned char* lds, const Gemm g, const StaticOrder& S, const Epi& E) {
;     ...
;     f32x4 acc[2][2][4][2];
; #pragma unroll
;     for (int a = 0; a < 2; ++a)
; #pragma unroll
;         for (int b = 0; b < 2; ++b)
; #pragma unroll
;             for (int m = 0; m < 4; ++m)
; #pragma unroll
;                 for (int n = 0; n < 2; ++n) acc[a][b][m][n] = (f32x4){0.f, 0.f, 0.f, 0.f};
;     bf16x8 At[4][2], B0[2][2], B1[2][2];
;     const char* cA = (const char*)g.A + (size_t)cur.pm * tstepA; const char* cB = (const char*)g.Bt + (size_t)cur.pn * tstepB;
;     PG8_STAGE(PG8_SB(0, 0), cB, voffB); PG8_STAGE(PG8_SB(0, 1), cB + hstepB, voffB); PG8_STAGE(PG8_SA(0, 0), cA, voffA); PG8_STAGE(PG8_SA(0, 1), cA + hstepA, voffA);
;     if (wr == 1) PG8_BAR;
;     PG8_WAIT_V(2); PG8_BAR;
;     PG8_STAGE(PG8_SB(1, 0), cB + kstep, voffB); PG8_STAGE(PG8_SA(1, 0), cA + kstep, voffA); PG8_STAGE(PG8_SB(1, 1), cB + hstepB + kstep, voffB);
;     PG8_WAIT_V(6); PG8_BAR;
;     for (;;) {
;         const bool has_next = S.next(ui + 1, nxt);
;         const char* nA = has_next ? (const char*)g.A + (size_t)nxt.pm * tstepA : cA; const char* nB = has_next ? (const char*)g.Bt + (size_t)nxt.pn * tstepB : cB;
;     ...
; #pragma unroll
;         for (int a = 0; a < 2; ++a)
; #pragma unroll
;             for (int b = 0; b < 2; ++b)
; #pragma unroll
;                 for (int m = 0; m < 4; ++m)
; #pragma unroll
;                     for (int n = 0; n < 2; ++n) acc[a][b][m][n] = (f32x4){0.f, 0.f, 0.f, 0.f};
;         cur = nxt; cA = nA; cB = nB; ++ui;
.LBB0_899:
	s_ashr_i32 s25, s24, 31
	s_lshl_b64 s[20:21], s[24:25], 20
	s_add_u32 s38, s64, s20
	v_mov_b32_e32 v123, 0
	s_addc_u32 s39, s65, s21
	s_andn2_b64 vcc, exec, s[14:15]
	v_mov_b32_e32 v122, v123
	v_mov_b32_e32 v121, v123
	v_mov_b32_e32 v120, v123
	v_mov_b32_e32 v127, v123
	v_mov_b32_e32 v126, v123
	v_mov_b32_e32 v125, v123
	v_mov_b32_e32 v124, v123
	v_mov_b32_e32 v111, v123
	v_mov_b32_e32 v110, v123
	v_mov_b32_e32 v109, v123
	v_mov_b32_e32 v108, v123
	v_mov_b32_e32 v107, v123
	v_mov_b32_e32 v106, v123
	v_mov_b32_e32 v105, v123
	v_mov_b32_e32 v104, v123
	v_mov_b32_e32 v95, v123
	v_mov_b32_e32 v94, v123
	v_mov_b32_e32 v93, v123
	v_mov_b32_e32 v92, v123
	v_mov_b32_e32 v91, v123
	v_mov_b32_e32 v90, v123
	v_mov_b32_e32 v89, v123
	v_mov_b32_e32 v88, v123
	v_mov_b32_e32 v79, v123
	v_mov_b32_e32 v78, v123
	v_mov_b32_e32 v77, v123
	v_mov_b32_e32 v76, v123
	v_mov_b32_e32 v75, v123
	v_mov_b32_e32 v74, v123
	v_mov_b32_e32 v73, v123
	v_mov_b32_e32 v72, v123
	v_mov_b32_e32 v119, v123
	v_mov_b32_e32 v118, v123
	v_mov_b32_e32 v117, v123
	v_mov_b32_e32 v116, v123
	v_mov_b32_e32 v115, v123
	v_mov_b32_e32 v114, v123
	v_mov_b32_e32 v113, v123
	v_mov_b32_e32 v112, v123
	v_mov_b32_e32 v103, v123
	v_mov_b32_e32 v102, v123
	v_mov_b32_e32 v101, v123
	v_mov_b32_e32 v100, v123
	v_mov_b32_e32 v99, v123
	v_mov_b32_e32 v98, v123
	v_mov_b32_e32 v97, v123
	v_mov_b32_e32 v96, v123
	v_mov_b32_e32 v87, v123
	v_mov_b32_e32 v86, v123
	v_mov_b32_e32 v85, v123
	v_mov_b32_e32 v84, v123
	v_mov_b32_e32 v83, v123
	v_mov_b32_e32 v82, v123
	v_mov_b32_e32 v81, v123
	v_mov_b32_e32 v80, v123
	v_mov_b32_e32 v71, v123
	v_mov_b32_e32 v70, v123
	v_mov_b32_e32 v69, v123
	v_mov_b32_e32 v68, v123
	v_mov_b32_e32 v67, v123
	v_mov_b32_e32 v66, v123
	v_mov_b32_e32 v65, v123
	v_mov_b32_e32 v64, v123
	v_mov_b32_e32 v63, v123
	v_mov_b32_e32 v62, v123
	v_mov_b32_e32 v61, v123
	v_mov_b32_e32 v60, v123
	v_mov_b32_e32 v59, v123
	v_mov_b32_e32 v58, v123
	v_mov_b32_e32 v57, v123
	v_mov_b32_e32 v56, v123
	v_mov_b32_e32 v47, v123
	v_mov_b32_e32 v46, v123
	v_mov_b32_e32 v45, v123
	v_mov_b32_e32 v44, v123
	v_mov_b32_e32 v43, v123
	v_mov_b32_e32 v42, v123
	v_mov_b32_e32 v41, v123
	v_mov_b32_e32 v40, v123
	v_mov_b32_e32 v31, v123
	v_mov_b32_e32 v30, v123
	v_mov_b32_e32 v29, v123
	v_mov_b32_e32 v28, v123
	v_mov_b32_e32 v27, v123
	v_mov_b32_e32 v26, v123
	v_mov_b32_e32 v25, v123
	v_mov_b32_e32 v24, v123
	v_mov_b32_e32 v15, v123
	v_mov_b32_e32 v14, v123
	v_mov_b32_e32 v13, v123
	v_mov_b32_e32 v12, v123
	v_mov_b32_e32 v11, v123
	v_mov_b32_e32 v10, v123
	v_mov_b32_e32 v9, v123
	v_mov_b32_e32 v8, v123
	v_mov_b32_e32 v55, v123
	v_mov_b32_e32 v54, v123
	v_mov_b32_e32 v53, v123
	v_mov_b32_e32 v52, v123
	v_mov_b32_e32 v51, v123
	v_mov_b32_e32 v50, v123
	v_mov_b32_e32 v49, v123
	v_mov_b32_e32 v48, v123
	v_mov_b32_e32 v39, v123
	v_mov_b32_e32 v38, v123
	v_mov_b32_e32 v37, v123
	v_mov_b32_e32 v36, v123
	v_mov_b32_e32 v35, v123
	v_mov_b32_e32 v34, v123
	v_mov_b32_e32 v33, v123
	v_mov_b32_e32 v32, v123
	v_mov_b32_e32 v23, v123
	v_mov_b32_e32 v22, v123
	v_mov_b32_e32 v21, v123
	v_mov_b32_e32 v20, v123
	v_mov_b32_e32 v19, v123
	v_mov_b32_e32 v18, v123
	v_mov_b32_e32 v17, v123
	v_mov_b32_e32 v16, v123
	v_mov_b32_e32 v7, v123
	v_mov_b32_e32 v6, v123
	v_mov_b32_e32 v5, v123
	v_mov_b32_e32 v4, v123
	v_mov_b32_e32 v3, v123
	v_mov_b32_e32 v2, v123
	v_mov_b32_e32 v1, v123
	v_mov_b32_e32 v0, v123
	s_cbranch_vccnz .LBB0_902
	s_and_b64 s[4:5], s[4:5], exec
	s_cselect_b32 s25, s39, s43
	s_cselect_b32 s52, s38, s42
	s_add_u32 s4, s42, 0x80080
	s_addc_u32 s5, s43, 0
	s_add_u32 s42, s40, 0x100
	v_mov_b32_e32 v0, 0
	s_addc_u32 s43, s41, 0
	s_mov_b32 s40, 0
	v_mov_b32_e32 v1, v0
	v_mov_b64_e32 v[2:3], 0
	v_mov_b64_e32 v[4:5], 0
	v_mov_b64_e32 v[6:7], 0
	v_mov_b64_e32 v[16:17], 0
	v_mov_b64_e32 v[18:19], 0
	v_mov_b64_e32 v[20:21], 0
	v_mov_b64_e32 v[22:23], 0
	v_mov_b64_e32 v[32:33], 0
	v_mov_b64_e32 v[34:35], 0
	v_mov_b64_e32 v[36:37], 0
	v_mov_b64_e32 v[38:39], 0
	v_mov_b64_e32 v[48:49], 0
	v_mov_b64_e32 v[50:51], 0
	v_mov_b64_e32 v[52:53], 0
	v_mov_b64_e32 v[54:55], 0
	v_mov_b64_e32 v[8:9], 0
	v_mov_b64_e32 v[10:11], 0
	v_mov_b64_e32 v[12:13], 0
	v_mov_b64_e32 v[14:15], 0
	v_mov_b64_e32 v[24:25], 0
	v_mov_b64_e32 v[26:27], 0
	v_mov_b64_e32 v[28:29], 0
	v_mov_b64_e32 v[30:31], 0
	v_mov_b64_e32 v[40:41], 0
	v_mov_b64_e32 v[42:43], 0
	v_mov_b64_e32 v[44:45], 0
	v_mov_b64_e32 v[46:47], 0
	v_mov_b64_e32 v[56:57], 0
	v_mov_b64_e32 v[58:59], 0
	v_mov_b64_e32 v[60:61], 0
	v_mov_b64_e32 v[62:63], 0
	v_mov_b64_e32 v[64:65], 0
	v_mov_b64_e32 v[66:67], 0
	v_mov_b64_e32 v[68:69], 0
	v_mov_b64_e32 v[70:71], 0
	v_mov_b64_e32 v[80:81], 0
	v_mov_b64_e32 v[82:83], 0
	v_mov_b64_e32 v[84:85], 0
	v_mov_b64_e32 v[86:87], 0
	v_mov_b64_e32 v[96:97], 0
	v_mov_b64_e32 v[98:99], 0
	v_mov_b64_e32 v[100:101], 0
	v_mov_b64_e32 v[102:103], 0
	v_mov_b64_e32 v[112:113], 0
	v_mov_b64_e32 v[114:115], 0
	v_mov_b64_e32 v[116:117], 0
	v_mov_b64_e32 v[118:119], 0
	v_mov_b64_e32 v[72:73], 0
	v_mov_b64_e32 v[74:75], 0
	v_mov_b64_e32 v[76:77], 0
	v_mov_b64_e32 v[78:79], 0
	v_mov_b64_e32 v[88:89], 0
	v_mov_b64_e32 v[90:91], 0
	v_mov_b64_e32 v[92:93], 0
	v_mov_b64_e32 v[94:95], 0
	v_mov_b64_e32 v[104:105], 0
	v_mov_b64_e32 v[106:107], 0
	v_mov_b64_e32 v[108:109], 0
	v_mov_b64_e32 v[110:111], 0
	v_mov_b64_e32 v[124:125], 0
	v_mov_b64_e32 v[126:127], 0
	v_mov_b64_e32 v[120:121], 0
	v_mov_b64_e32 v[122:123], 0

; #define PG8_STAGE(bufoff, gbase, voff) do { _Pragma("unroll") for (int _i = 0; _i < 2; ++_i) \
;         __builtin_amdgcn_global_load_lds((const unsigned*)((const char*)(gbase) + (voff)[_i]), (LAS unsigned*)(lds + (bufoff) + ldsw + _i * 8192), 16, 0, 0); } while (0)
; #define PG8_WAIT_V(n) asm volatile("s_waitcnt vmcnt(" #n ")" ::: "memory")
; #define PG8_BAR __builtin_amdgcn_s_barrier()
; template <class Epi, bool ALIGN_EPI = PG8_ALIGN>
; __device__ __forceinline__ void gemm_phase(LAS unsigned char* lds, const Gemm g, const StaticOrder& S, const Epi& E) {
;     ...
;     f32x4 acc[2][2][4][2];
; #pragma unroll
;     for (int a = 0; a < 2; ++a)
; #pragma unroll
;         for (int b = 0; b < 2; ++b)
; #pragma unroll
;             for (int m = 0; m < 4; ++m)
; #pragma unroll
;                 for (int n = 0; n < 2; ++n) acc[a][b][m][n] = (f32x4){0.f, 0.f, 0.f, 0.f};
;     bf16x8 At[4][2], B0[2][2], B1[2][2];
;     const char* cA = (const char*)g.A + (size_t)cur.pm * tstepA; const char* cB = (const char*)g.Bt + (size_t)cur.pn * tstepB;
;     PG8_STAGE(PG8_SB(0, 0), cB, voffB); PG8_STAGE(PG8_SB(0, 1), cB + hstepB, voffB); PG8_STAGE(PG8_SA(0, 0), cA, voffA); PG8_STAGE(PG8_SA(0, 1), cA + hstepA, voffA);
;     if (wr == 1) PG8_BAR;
;     PG8_WAIT_V(2); PG8_BAR;
;     PG8_STAGE(PG8_SB(1, 0), cB + kstep, voffB); PG8_STAGE(PG8_SA(1, 0), cA + kstep, voffA); PG8_STAGE(PG8_SB(1, 1), cB + hstepB + kstep, voffB);
;     PG8_WAIT_V(6); PG8_BAR;
;     for (;;) {
;         const bool has_next = S.next(ui + 1, nxt);
;         const char* nA = has_next ? (const char*)g.A + (size_t)nxt.pm * tstepA : cA; const char* nB = has_next ? (const char*)g.Bt + (size_t)nxt.pn * tstepB : cB;
;     ...
; #pragma unroll
;         for (int a = 0; a < 2; ++a)
; #pragma unroll
;             for (int b = 0; b < 2; ++b)
; #pragma unroll
;                 for (int m = 0; m < 4; ++m)
; #pragma unroll
;                     for (int n = 0; n < 2; ++n) acc[a][b][m][n] = (f32x4){0.f, 0.f, 0.f, 0.f};
;         cur = nxt; cA = nA; cB = nB; ++ui;
.LBB0_1026:
	s_ashr_i32 s17, s16, 31
	s_lshl_b64 s[20:21], s[16:17], 20
	s_add_u32 s42, s58, s20
	v_mov_b32_e32 v127, 0
	s_addc_u32 s43, s59, s21
	s_andn2_b64 vcc, exec, s[12:13]
	v_mov_b32_e32 v126, v127
	v_mov_b32_e32 v125, v127
	v_mov_b32_e32 v124, v127
	v_mov_b32_e32 v119, v127
	v_mov_b32_e32 v118, v127
	v_mov_b32_e32 v117, v127
	v_mov_b32_e32 v116, v127
	v_mov_b32_e32 v111, v127
	v_mov_b32_e32 v110, v127
	v_mov_b32_e32 v109, v127
	v_mov_b32_e32 v108, v127
	v_mov_b32_e32 v103, v127
	v_mov_b32_e32 v102, v127
	v_mov_b32_e32 v101, v127
	v_mov_b32_e32 v100, v127
	v_mov_b32_e32 v95, v127
	v_mov_b32_e32 v94, v127
	v_mov_b32_e32 v93, v127
	v_mov_b32_e32 v92, v127
	v_mov_b32_e32 v87, v127
	v_mov_b32_e32 v86, v127
	v_mov_b32_e32 v85, v127
	v_mov_b32_e32 v84, v127
	v_mov_b32_e32 v79, v127
	v_mov_b32_e32 v78, v127
	v_mov_b32_e32 v77, v127
	v_mov_b32_e32 v76, v127
	v_mov_b32_e32 v71, v127
	v_mov_b32_e32 v70, v127
	v_mov_b32_e32 v69, v127
	v_mov_b32_e32 v68, v127
	v_mov_b32_e32 v123, v127
	v_mov_b32_e32 v122, v127
	v_mov_b32_e32 v121, v127
	v_mov_b32_e32 v120, v127
	v_mov_b32_e32 v115, v127
	v_mov_b32_e32 v114, v127
	v_mov_b32_e32 v113, v127
	v_mov_b32_e32 v112, v127
	v_mov_b32_e32 v107, v127
	v_mov_b32_e32 v106, v127
	v_mov_b32_e32 v105, v127
	v_mov_b32_e32 v104, v127
	v_mov_b32_e32 v99, v127
	v_mov_b32_e32 v98, v127
	v_mov_b32_e32 v97, v127
	v_mov_b32_e32 v96, v127
	v_mov_b32_e32 v91, v127
	v_mov_b32_e32 v90, v127
	v_mov_b32_e32 v89, v127
	v_mov_b32_e32 v88, v127
	v_mov_b32_e32 v83, v127
	v_mov_b32_e32 v82, v127
	v_mov_b32_e32 v81, v127
	v_mov_b32_e32 v80, v127
	v_mov_b32_e32 v75, v127
	v_mov_b32_e32 v74, v127
	v_mov_b32_e32 v73, v127
	v_mov_b32_e32 v72, v127
	v_mov_b32_e32 v67, v127
	v_mov_b32_e32 v66, v127
	v_mov_b32_e32 v65, v127
	v_mov_b32_e32 v64, v127
	v_mov_b32_e32 v63, v127
	v_mov_b32_e32 v62, v127
	v_mov_b32_e32 v61, v127
	v_mov_b32_e32 v60, v127
	v_mov_b32_e32 v55, v127
	v_mov_b32_e32 v54, v127
	v_mov_b32_e32 v53, v127
	v_mov_b32_e32 v52, v127
	v_mov_b32_e32 v47, v127
	v_mov_b32_e32 v46, v127
	v_mov_b32_e32 v45, v127
	v_mov_b32_e32 v44, v127
	v_mov_b32_e32 v39, v127
	v_mov_b32_e32 v38, v127
	v_mov_b32_e32 v37, v127
	v_mov_b32_e32 v36, v127
	v_mov_b32_e32 v31, v127
	v_mov_b32_e32 v30, v127
	v_mov_b32_e32 v29, v127
	v_mov_b32_e32 v28, v127
	v_mov_b32_e32 v23, v127
	v_mov_b32_e32 v22, v127
	v_mov_b32_e32 v21, v127
	v_mov_b32_e32 v20, v127
	v_mov_b32_e32 v15, v127
	v_mov_b32_e32 v14, v127
	v_mov_b32_e32 v13, v127
	v_mov_b32_e32 v12, v127
	v_mov_b32_e32 v7, v127
	v_mov_b32_e32 v6, v127
	v_mov_b32_e32 v5, v127
	v_mov_b32_e32 v4, v127
	v_mov_b32_e32 v59, v127
	v_mov_b32_e32 v58, v127
	v_mov_b32_e32 v57, v127
	v_mov_b32_e32 v56, v127
	v_mov_b32_e32 v51, v127
	v_mov_b32_e32 v50, v127
	v_mov_b32_e32 v49, v127
	v_mov_b32_e32 v48, v127
	v_mov_b32_e32 v43, v127
	v_mov_b32_e32 v42, v127
	v_mov_b32_e32 v41, v127
	v_mov_b32_e32 v40, v127
	v_mov_b32_e32 v35, v127
	v_mov_b32_e32 v34, v127
	v_mov_b32_e32 v33, v127
	v_mov_b32_e32 v32, v127
	v_mov_b32_e32 v27, v127
	v_mov_b32_e32 v26, v127
	v_mov_b32_e32 v25, v127
	v_mov_b32_e32 v24, v127
	v_mov_b32_e32 v19, v127
	v_mov_b32_e32 v18, v127
	v_mov_b32_e32 v17, v127
	v_mov_b32_e32 v16, v127
	v_mov_b32_e32 v11, v127
	v_mov_b32_e32 v10, v127
	v_mov_b32_e32 v9, v127
	v_mov_b32_e32 v8, v127
	v_mov_b32_e32 v3, v127
	v_mov_b32_e32 v2, v127
	v_mov_b32_e32 v1, v127
	v_mov_b32_e32 v0, v127
	s_cbranch_vccnz .LBB0_1029
	s_and_b64 s[2:3], s[2:3], exec
	s_cselect_b32 s17, s43, s37
	s_cselect_b32 s27, s42, s36
	s_add_u32 s2, s36, 0x80080
	s_addc_u32 s3, s37, 0
	s_add_u32 s29, s24, 0x100
	v_mov_b32_e32 v0, 0
	s_addc_u32 s30, s25, 0
	s_mov_b32 s24, 0
	v_mov_b32_e32 v1, v0
	v_mov_b64_e32 v[2:3], 0
	v_mov_b64_e32 v[8:9], 0
	v_mov_b64_e32 v[10:11], 0
	v_mov_b64_e32 v[16:17], 0
	v_mov_b64_e32 v[18:19], 0
	v_mov_b64_e32 v[24:25], 0
	v_mov_b64_e32 v[26:27], 0
	v_mov_b64_e32 v[32:33], 0
	v_mov_b64_e32 v[34:35], 0
	v_mov_b64_e32 v[40:41], 0
	v_mov_b64_e32 v[42:43], 0
	v_mov_b64_e32 v[48:49], 0
	v_mov_b64_e32 v[50:51], 0
	v_mov_b64_e32 v[56:57], 0
	v_mov_b64_e32 v[58:59], 0
	v_mov_b64_e32 v[4:5], 0
	v_mov_b64_e32 v[6:7], 0
	v_mov_b64_e32 v[12:13], 0
	v_mov_b64_e32 v[14:15], 0
	v_mov_b64_e32 v[20:21], 0
	v_mov_b64_e32 v[22:23], 0
	v_mov_b64_e32 v[28:29], 0
	v_mov_b64_e32 v[30:31], 0
	v_mov_b64_e32 v[36:37], 0
	v_mov_b64_e32 v[38:39], 0
	v_mov_b64_e32 v[44:45], 0
	v_mov_b64_e32 v[46:47], 0
	v_mov_b64_e32 v[52:53], 0
	v_mov_b64_e32 v[54:55], 0
	v_mov_b64_e32 v[60:61], 0
	v_mov_b64_e32 v[62:63], 0
	v_mov_b64_e32 v[64:65], 0
	v_mov_b64_e32 v[66:67], 0
	v_mov_b64_e32 v[72:73], 0
	v_mov_b64_e32 v[74:75], 0
	v_mov_b64_e32 v[80:81], 0
	v_mov_b64_e32 v[82:83], 0
	v_mov_b64_e32 v[88:89], 0
	v_mov_b64_e32 v[90:91], 0
	v_mov_b64_e32 v[96:97], 0
	v_mov_b64_e32 v[98:99], 0
	v_mov_b64_e32 v[104:105], 0
	v_mov_b64_e32 v[106:107], 0
	v_mov_b64_e32 v[112:113], 0
	v_mov_b64_e32 v[114:115], 0
	v_mov_b64_e32 v[120:121], 0
	v_mov_b64_e32 v[122:123], 0
	v_mov_b64_e32 v[68:69], 0
	v_mov_b64_e32 v[70:71], 0
	v_mov_b64_e32 v[76:77], 0
	v_mov_b64_e32 v[78:79], 0
	v_mov_b64_e32 v[84:85], 0
	v_mov_b64_e32 v[86:87], 0
	v_mov_b64_e32 v[92:93], 0
	v_mov_b64_e32 v[94:95], 0
	v_mov_b64_e32 v[100:101], 0
	v_mov_b64_e32 v[102:103], 0
	v_mov_b64_e32 v[108:109], 0
	v_mov_b64_e32 v[110:111], 0
	v_mov_b64_e32 v[116:117], 0
	v_mov_b64_e32 v[118:119], 0
	v_mov_b64_e32 v[124:125], 0
	v_mov_b64_e32 v[126:127], 0

; #define PG8_STAGE(bufoff, gbase, voff) do { _Pragma("unroll") for (int _i = 0; _i < 2; ++_i) \
;         __builtin_amdgcn_global_load_lds((const unsigned*)((const char*)(gbase) + (voff)[_i]), (LAS unsigned*)(lds + (bufoff) + ldsw + _i * 8192), 16, 0, 0); } while (0)
; #define PG8_WAIT_V(n) asm volatile("s_waitcnt vmcnt(" #n ")" ::: "memory")
; #define PG8_BAR __builtin_amdgcn_s_barrier()
; template <class Epi, bool ALIGN_EPI = PG8_ALIGN>
; __device__ __forceinline__ void gemm_phase(LAS unsigned char* lds, const Gemm g, const StaticOrder& S, const Epi& E) {
;     ...
;     f32x4 acc[2][2][4][2];
; #pragma unroll
;     for (int a = 0; a < 2; ++a)
; #pragma unroll
;         for (int b = 0; b < 2; ++b)
; #pragma unroll
;             for (int m = 0; m < 4; ++m)
; #pragma unroll
;                 for (int n = 0; n < 2; ++n) acc[a][b][m][n] = (f32x4){0.f, 0.f, 0.f, 0.f};
;     bf16x8 At[4][2], B0[2][2], B1[2][2];
;     const char* cA = (const char*)g.A + (size_t)cur.pm * tstepA; const char* cB = (const char*)g.Bt + (size_t)cur.pn * tstepB;
;     PG8_STAGE(PG8_SB(0, 0), cB, voffB); PG8_STAGE(PG8_SB(0, 1), cB + hstepB, voffB); PG8_STAGE(PG8_SA(0, 0), cA, voffA); PG8_STAGE(PG8_SA(0, 1), cA + hstepA, voffA);
;     if (wr == 1) PG8_BAR;
;     PG8_WAIT_V(2); PG8_BAR;
;     PG8_STAGE(PG8_SB(1, 0), cB + kstep, voffB); PG8_STAGE(PG8_SA(1, 0), cA + kstep, voffA); PG8_STAGE(PG8_SB(1, 1), cB + hstepB + kstep, voffB);
;     PG8_WAIT_V(6); PG8_BAR;
;     for (;;) {
;         const bool has_next = S.next(ui + 1, nxt);
;         const char* nA = has_next ? (const char*)g.A + (size_t)nxt.pm * tstepA : cA; const char* nB = has_next ? (const char*)g.Bt + (size_t)nxt.pn * tstepB : cB;
;     ...
; #pragma unroll
;         for (int a = 0; a < 2; ++a)
; #pragma unroll
;             for (int b = 0; b < 2; ++b)
; #pragma unroll
;                 for (int m = 0; m < 4; ++m)
; #pragma unroll
;                     for (int n = 0; n < 2; ++n) acc[a][b][m][n] = (f32x4){0.f, 0.f, 0.f, 0.f};
;         cur = nxt; cA = nA; cB = nB; ++ui;
.LBB0_1106:
	v_mov_b32_e32 v127, 0
	s_andn2_b64 vcc, exec, s[12:13]
	v_mov_b32_e32 v126, 0
	v_mov_b32_e32 v125, 0
	v_mov_b32_e32 v124, 0
	v_mov_b32_e32 v123, 0
	v_mov_b32_e32 v122, 0
	v_mov_b32_e32 v121, 0
	v_mov_b32_e32 v120, 0
	v_mov_b32_e32 v101, 0
	v_mov_b32_e32 v100, 0
	v_mov_b32_e32 v103, 0
	v_mov_b32_e32 v102, 0
	v_mov_b32_e32 v109, 0
	v_mov_b32_e32 v108, 0
	v_mov_b32_e32 v111, 0
	v_mov_b32_e32 v110, 0
	v_mov_b32_e32 v85, 0
	v_mov_b32_e32 v84, 0
	v_mov_b32_e32 v87, 0
	v_mov_b32_e32 v86, 0
	v_mov_b32_e32 v93, 0
	v_mov_b32_e32 v92, 0
	v_mov_b32_e32 v95, 0
	v_mov_b32_e32 v94, 0
	v_mov_b32_e32 v73, 0
	v_mov_b32_e32 v72, 0
	v_mov_b32_e32 v75, 0
	v_mov_b32_e32 v74, 0
	v_mov_b32_e32 v77, 0
	v_mov_b32_e32 v76, 0
	v_mov_b32_e32 v79, 0
	v_mov_b32_e32 v78, 0
	v_mov_b32_e32 v139, 0
	v_mov_b32_e32 v138, 0
	v_mov_b32_e32 v141, 0
	v_mov_b32_e32 v140, 0
	v_mov_b32_e32 v143, 0
	v_mov_b32_e32 v142, 0
	v_mov_b32_e32 v145, 0
	v_mov_b32_e32 v144, 0
	v_mov_b32_e32 v113, 0
	v_mov_b32_e32 v112, 0
	v_mov_b32_e32 v115, 0
	v_mov_b32_e32 v114, 0
	v_mov_b32_e32 v117, 0
	v_mov_b32_e32 v116, 0
	v_mov_b32_e32 v119, 0
	v_mov_b32_e32 v118, 0
	v_mov_b32_e32 v97, 0
	v_mov_b32_e32 v96, 0
	v_mov_b32_e32 v99, 0
	v_mov_b32_e32 v98, 0
	v_mov_b32_e32 v105, 0
	v_mov_b32_e32 v104, 0
	v_mov_b32_e32 v107, 0
	v_mov_b32_e32 v106, 0
	v_mov_b32_e32 v71, 0
	v_mov_b32_e32 v70, 0
	v_mov_b32_e32 v69, 0
	v_mov_b32_e32 v68, 0
	v_mov_b32_e32 v67, 0
	v_mov_b32_e32 v66, 0
	v_mov_b32_e32 v65, 0
	v_mov_b32_e32 v64, 0
	v_mov_b32_e32 v63, 0
	v_mov_b32_e32 v62, 0
	v_mov_b32_e32 v61, 0
	v_mov_b32_e32 v60, 0
	v_mov_b32_e32 v59, 0
	v_mov_b32_e32 v58, 0
	v_mov_b32_e32 v57, 0
	v_mov_b32_e32 v56, 0
	v_mov_b32_e32 v37, 0
	v_mov_b32_e32 v36, 0
	v_mov_b32_e32 v39, 0
	v_mov_b32_e32 v38, 0
	v_mov_b32_e32 v45, 0
	v_mov_b32_e32 v44, 0
	v_mov_b32_e32 v47, 0
	v_mov_b32_e32 v46, 0
	v_mov_b32_e32 v21, 0
	v_mov_b32_e32 v20, 0
	v_mov_b32_e32 v23, 0
	v_mov_b32_e32 v22, 0
	v_mov_b32_e32 v29, 0
	v_mov_b32_e32 v28, 0
	v_mov_b32_e32 v31, 0
	v_mov_b32_e32 v30, 0
	v_mov_b32_e32 v9, 0
	v_mov_b32_e32 v8, 0
	v_mov_b32_e32 v11, 0
	v_mov_b32_e32 v10, 0
	v_mov_b32_e32 v13, 0
	v_mov_b32_e32 v12, 0
	v_mov_b32_e32 v15, 0
	v_mov_b32_e32 v14, 0
	v_mov_b32_e32 v81, 0
	v_mov_b32_e32 v80, 0
	v_mov_b32_e32 v83, 0
	v_mov_b32_e32 v82, 0
	v_mov_b32_e32 v89, 0
	v_mov_b32_e32 v88, 0
	v_mov_b32_e32 v91, 0
	v_mov_b32_e32 v90, 0
	v_mov_b32_e32 v49, 0
	v_mov_b32_e32 v48, 0
	v_mov_b32_e32 v51, 0
	v_mov_b32_e32 v50, 0
	v_mov_b32_e32 v53, 0
	v_mov_b32_e32 v52, 0
	v_mov_b32_e32 v55, 0
	v_mov_b32_e32 v54, 0
	v_mov_b32_e32 v33, 0
	v_mov_b32_e32 v32, 0
	v_mov_b32_e32 v35, 0
	v_mov_b32_e32 v34, 0
	v_mov_b32_e32 v41, 0
	v_mov_b32_e32 v40, 0
	v_mov_b32_e32 v43, 0
	v_mov_b32_e32 v42, 0
	v_mov_b32_e32 v7, 0
	v_mov_b32_e32 v6, 0
	v_mov_b32_e32 v5, 0
	v_mov_b32_e32 v4, 0
	v_mov_b32_e32 v3, 0
	v_mov_b32_e32 v2, 0
	v_mov_b32_e32 v1, 0
	v_mov_b32_e32 v0, 0
	s_cbranch_vccnz .LBB0_1110
	s_add_u32 s51, s36, 0x100
	v_mov_b32_e32 v0, 0
	s_addc_u32 s52, s37, 0
	s_mov_b32 s40, 0
	v_mov_b32_e32 v1, v0
	v_mov_b64_e32 v[2:3], 0
	v_mov_b64_e32 v[4:5], 0
	v_mov_b64_e32 v[6:7], 0
	v_mov_b64_e32 v[8:9], 0
	v_mov_b64_e32 v[10:11], 0
	v_mov_b64_e32 v[12:13], 0
	v_mov_b64_e32 v[14:15], 0
	v_mov_b64_e32 v[20:21], 0
	v_mov_b64_e32 v[22:23], 0
	v_mov_b64_e32 v[28:29], 0
	v_mov_b64_e32 v[30:31], 0
	v_mov_b64_e32 v[36:37], 0
	v_mov_b64_e32 v[38:39], 0
	v_mov_b64_e32 v[44:45], 0
	v_mov_b64_e32 v[46:47], 0
	v_mov_b64_e32 v[16:17], 0
	v_mov_b64_e32 v[18:19], 0
	v_mov_b64_e32 v[24:25], 0
	v_mov_b64_e32 v[26:27], 0
	v_mov_b64_e32 v[32:33], 0
	v_mov_b64_e32 v[34:35], 0
	v_mov_b64_e32 v[40:41], 0
	v_mov_b64_e32 v[42:43], 0
	v_mov_b64_e32 v[48:49], 0
	v_mov_b64_e32 v[50:51], 0
	v_mov_b64_e32 v[52:53], 0
	v_mov_b64_e32 v[54:55], 0
	v_mov_b64_e32 v[56:57], 0
	v_mov_b64_e32 v[58:59], 0
	v_mov_b64_e32 v[60:61], 0
	v_mov_b64_e32 v[62:63], 0
	v_mov_b64_e32 v[64:65], 0
	v_mov_b64_e32 v[66:67], 0
	v_mov_b64_e32 v[68:69], 0
	v_mov_b64_e32 v[70:71], 0
	v_mov_b64_e32 v[72:73], 0
	v_mov_b64_e32 v[74:75], 0
	v_mov_b64_e32 v[76:77], 0
	v_mov_b64_e32 v[78:79], 0
	v_mov_b64_e32 v[84:85], 0
	v_mov_b64_e32 v[86:87], 0
	v_mov_b64_e32 v[92:93], 0
	v_mov_b64_e32 v[94:95], 0
	v_mov_b64_e32 v[100:101], 0
	v_mov_b64_e32 v[102:103], 0
	v_mov_b64_e32 v[108:109], 0
	v_mov_b64_e32 v[110:111], 0
	v_mov_b64_e32 v[80:81], 0
	v_mov_b64_e32 v[82:83], 0
	v_mov_b64_e32 v[88:89], 0
	v_mov_b64_e32 v[90:91], 0
	v_mov_b64_e32 v[96:97], 0
	v_mov_b64_e32 v[98:99], 0
	v_mov_b64_e32 v[104:105], 0
	v_mov_b64_e32 v[106:107], 0
	v_mov_b64_e32 v[112:113], 0
	v_mov_b64_e32 v[114:115], 0
	v_mov_b64_e32 v[116:117], 0
	v_mov_b64_e32 v[118:119], 0
	v_mov_b64_e32 v[120:121], 0
	v_mov_b64_e32 v[122:123], 0
	v_mov_b64_e32 v[124:125], 0
	v_mov_b64_e32 v[126:127], 0
